# attention: loop-top LDS-write drain+barrier moved after next-task prefetch issue (all 3 modes); mode2 sink value via s_load (removes vmcnt(0) that serialized prefetch with compute)
# baseline (speedup 1.0000x reference)
.LBB0_454:
	s_add_i32 s0, s63, 1
	v_cvt_f32_u32_e32 v4, s0
	v_add_u32_e32 v0, v164, v171
	s_waitcnt vmcnt(13)
	ds_write_b128 v0, v[84:87]
	s_waitcnt vmcnt(12)
	ds_write_b128 v0, v[80:83] offset:55296
	ds_write_b128 v0, v[96:99] offset:9216
	ds_write_b128 v0, v[92:95] offset:64512
	s_waitcnt vmcnt(4)
	ds_write_b128 v0, v[104:107] offset:18432
	ds_write_b128 v174, v[100:103] offset:18432
	ds_write_b128 v0, v[120:123] offset:27648
	ds_write_b128 v174, v[112:115] offset:27648
	ds_write_b128 v0, v[124:127] offset:36864
	ds_write_b128 v174, v[108:111] offset:36864
	ds_write_b128 v0, v[128:131] offset:46080
	ds_write_b128 v174, v[116:119] offset:46080
	ds_write_b128 v185, v[136:139]
	s_mov_b32 s0, 0xc2fc0000
	v_mul_f32_e32 v0, -0.5, v4
	v_cmp_gt_f32_e64 s[6:7], s0, v0
	s_and_b64 s[0:1], s[6:7], exec
	s_cselect_b32 s96, 0xffffffc0, 0
	s_add_i32 s88, s42, s88
	s_cmpk_gt_i32 s88, 0xfff
	s_cselect_b64 s[58:59], -1, 0
	s_and_b64 vcc, exec, s[58:59]
	s_mov_b32 s93, s16
	ds_write_b128 v185, v[132:135] offset:1152
	ds_write_b128 v185, v[144:147] offset:2304
	ds_write_b128 v185, v[140:143] offset:3456
	s_cbranch_vccnz .LBB0_461
	s_and_b32 s0, s88, 0x7ff
	s_cmpk_lt_u32 s88, 0x800
	s_cselect_b32 s89, 16, 4
	s_cselect_b32 s1, 0, 3
	s_cselect_b32 s18, 0, 2
	s_cselect_b32 s94, 4, 2
	s_and_b32 s79, s1, s88
	s_lshr_b32 s0, s0, s18
	s_add_i32 s1, s89, -1
	s_and_b32 s90, s0, s1
	s_lshr_b32 s0, s0, s94
	s_and_b32 s92, s0, 15
	s_lshr_b32 s93, s0, 4
	s_lshl_b32 s0, s93, 18
	s_lshl_b32 s1, s92, 21
	s_add_i32 s1, s1, s0
	s_lshl_b32 s91, s79, 8
	s_lshl_b32 s97, s1, 1
	s_add_u32 vcc_lo, s8, s97
	s_addc_u32 vcc_hi, s9, 0
	s_add_u32 s18, s10, s97
	s_addc_u32 s19, s11, 0
	v_lshlrev_b32_e32 v0, s94, v160
	v_lshl_or_b32 v88, v0, 7, v161
	s_cmp_lg_u32 s79, 0
	s_cselect_b64 s[0:1], -1, 0
	s_cmp_eq_u32 s79, 0
	v_lshl_add_u64 v[0:1], vcc, 0, v[88:89]
	v_lshl_add_u64 v[2:3], s[18:19], 0, v[88:89]
	s_cbranch_scc1 .LBB0_458
	s_add_i32 s18, s91, 0xffffff80
	s_ashr_i32 s19, s18, 31
	s_lshl_b64 s[18:19], s[18:19], s94
	s_add_u32 s18, s18, s90
	s_addc_u32 s19, s19, 0
	s_lshl_b64 s[18:19], s[18:19], 7
	v_lshl_add_u64 v[6:7], v[0:1], 0, s[18:19]
	v_lshl_add_u64 v[8:9], v[2:3], 0, s[18:19]
	global_load_dwordx4 v[84:87], v[6:7], off nt
	global_load_dwordx4 v[80:83], v[8:9], off nt
	s_andn2_b64 vcc, exec, s[0:1]
	s_cbranch_vccnz .LBB0_459

.LBB0_461:
	s_waitcnt lgkmcnt(0)
	s_barrier
	v_cndmask_b32_e64 v0, 0, v186, s[6:7]
	v_fmac_f32_e32 v0, -0.5, v4
	v_exp_f32_e32 v0, v0
	v_cvt_f32_u32_e32 v188, s60
	v_mul_u32_u24_e32 v88, s60, v165
	s_add_i32 s6, s95, s62
	v_ldexp_f32 v0, v0, s96
	v_mul_f32_e32 v0, v0, v188
	v_mul_f32_e32 v72, 0x3fb8aa3b, v0
	v_add_u32_e32 v0, v166, v167
	v_mov_b32_e32 v189, v168
	ds_read_b128 v[190:193], v0
	ds_read_b128 v[156:159], v0 offset:32
	ds_read_b128 v[152:155], v0 offset:64
	ds_read_b128 v[148:151], v0 offset:96
	s_cmpk_gt_i32 s6, 0x7f
	v_cvt_f32_i32_e32 v0, v189
	v_mul_f32_e32 v9, 0, v72
	s_cselect_b64 vcc, -1, 0
	v_cndmask_b32_e32 v10, v187, v9, vcc
	v_mul_f32_e64 v8, -v72, v0
	v_fma_f32 v91, -v72, v0, v72
	ds_read_b128 v[0:3], v175
	ds_read_b128 v[4:7], v175 offset:32
	v_fma_f32 v90, 0, v72, v8
	v_pk_fma_f32 v[202:203], v[72:73], s[36:37], v[8:9] op_sel_hi:[0,1,0]
	v_pk_fma_f32 v[204:205], v[72:73], s[44:45], v[8:9] op_sel_hi:[0,1,0]
	v_pk_fma_f32 v[206:207], v[72:73], s[46:47], v[8:9] op_sel_hi:[0,1,0]
	v_pk_fma_f32 v[208:209], v[72:73], s[48:49], v[8:9] op_sel_hi:[0,1,0]
	v_pk_fma_f32 v[74:75], v[72:73], s[52:53], v[8:9] op_sel_hi:[0,1,0]
	v_pk_fma_f32 v[76:77], v[72:73], s[54:55], v[8:9] op_sel_hi:[0,1,0]
	v_pk_fma_f32 v[78:79], v[72:73], s[56:57], v[8:9] op_sel_hi:[0,1,0]
	v_pk_add_f32 v[62:63], v[10:11], v[78:79] op_sel_hi:[0,1]
	v_pk_add_f32 v[60:61], v[10:11], v[76:77] op_sel_hi:[0,1]
	v_pk_add_f32 v[58:59], v[10:11], v[74:75] op_sel_hi:[0,1]
	v_pk_add_f32 v[56:57], v[10:11], v[208:209] op_sel_hi:[0,1]
	v_pk_add_f32 v[54:55], v[10:11], v[206:207] op_sel_hi:[0,1]
	v_pk_add_f32 v[52:53], v[10:11], v[204:205] op_sel_hi:[0,1]
	v_pk_add_f32 v[50:51], v[10:11], v[202:203] op_sel_hi:[0,1]
	v_pk_add_f32 v[48:49], v[10:11], v[90:91] op_sel_hi:[0,1]
	s_cmpk_gt_i32 s6, 0x5f
	v_mul_f32_e32 v12, 0x42000000, v72
	s_waitcnt lgkmcnt(1)
	v_mfma_f32_32x32x16_bf16 v[48:63], v[0:3], v[190:193], v[48:63]
	s_cselect_b64 vcc, -1, 0
	v_cndmask_b32_e32 v12, v187, v12, vcc
	v_add_f32_e64 v46, v12, v78
	v_add_f32_e64 v47, v12, v79
	v_add_f32_e64 v44, v12, v76
	v_add_f32_e64 v45, v12, v77
	v_pk_add_f32 v[42:43], v[12:13], v[74:75] op_sel_hi:[0,1]
	v_pk_add_f32 v[40:41], v[12:13], v[208:209] op_sel_hi:[0,1]
	v_pk_add_f32 v[38:39], v[12:13], v[206:207] op_sel_hi:[0,1]
	s_waitcnt lgkmcnt(0)
	v_mfma_f32_32x32x16_bf16 v[48:63], v[4:7], v[156:159], v[48:63]
	ds_read_b128 v[0:3], v175 offset:64
	ds_read_b128 v[4:7], v175 offset:96
	v_add_f32_e64 v36, v12, v204
	v_add_f32_e64 v37, v12, v205
	v_add_f32_e64 v34, v12, v202
	v_add_f32_e64 v35, v12, v203
	v_pk_add_f32 v[32:33], v[12:13], v[90:91] op_sel_hi:[0,1]
	s_cmp_gt_i32 s6, 63
	v_mul_f32_e32 v12, 0x42800000, v72
	s_cselect_b64 vcc, -1, 0
	s_waitcnt lgkmcnt(1)
	v_mfma_f32_32x32x16_bf16 v[48:63], v[0:3], v[152:155], v[48:63]
	ds_read_b128 v[0:3], v176
	ds_read_b128 v[8:11], v176 offset:32
	v_cndmask_b32_e32 v12, v187, v12, vcc
	v_add_f32_e64 v30, v12, v78
	v_add_f32_e64 v31, v12, v79
	v_pk_add_f32 v[28:29], v[12:13], v[76:77] op_sel_hi:[0,1]
	v_pk_add_f32 v[26:27], v[12:13], v[74:75] op_sel_hi:[0,1]
	v_pk_add_f32 v[24:25], v[12:13], v[208:209] op_sel_hi:[0,1]
	v_pk_add_f32 v[22:23], v[12:13], v[206:207] op_sel_hi:[0,1]
	s_waitcnt lgkmcnt(1)
	v_mfma_f32_32x32x16_bf16 v[32:47], v[0:3], v[190:193], v[32:47]
	v_add_f32_e64 v20, v12, v204
	v_add_f32_e64 v21, v12, v205
	v_add_f32_e64 v18, v12, v202
	v_add_f32_e64 v19, v12, v203
	v_add_f32_e64 v16, v12, v90
	v_add_f32_e64 v17, v12, v91
	s_cmp_gt_i32 s6, 31
	s_cselect_b64 vcc, -1, 0
	s_cmp_gt_i32 s6, -1
	s_waitcnt lgkmcnt(0)
	v_mfma_f32_32x32x16_bf16 v[32:47], v[8:11], v[156:159], v[32:47]
	v_mfma_f32_32x32x16_bf16 v[48:63], v[4:7], v[148:151], v[48:63]
	ds_read_b128 v[0:3], v176 offset:64
	ds_read_b128 v[4:7], v176 offset:96
	s_waitcnt lgkmcnt(1)
	v_mfma_f32_32x32x16_bf16 v[32:47], v[0:3], v[152:155], v[32:47]
	ds_read_b128 v[0:3], v177
	ds_read_b128 v[8:11], v177 offset:32
	s_waitcnt lgkmcnt(1)
	v_mfma_f32_32x32x16_bf16 v[16:31], v[0:3], v[190:193], v[16:31]
	s_waitcnt lgkmcnt(0)
	v_mfma_f32_32x32x16_bf16 v[16:31], v[8:11], v[156:159], v[16:31]
	v_mfma_f32_32x32x16_bf16 v[32:47], v[4:7], v[148:151], v[32:47]
	ds_read_b128 v[0:3], v177 offset:64
	ds_read_b128 v[4:7], v177 offset:96
	ds_read_b128 v[64:67], v178
	ds_read_b128 v[68:71], v178 offset:32
	s_waitcnt lgkmcnt(3)
	v_mfma_f32_32x32x16_bf16 v[16:31], v[0:3], v[152:155], v[16:31]
	v_mul_f32_e32 v0, 0x42c00000, v72
	v_cndmask_b32_e32 v0, v187, v0, vcc
	v_add_f32_e64 v14, v0, v78
	v_add_f32_e64 v15, v0, v79
	v_add_f32_e64 v12, v0, v76
	v_add_f32_e64 v13, v0, v77
	v_pk_add_f32 v[10:11], v[0:1], v[74:75] op_sel_hi:[0,1]
	v_pk_add_f32 v[8:9], v[0:1], v[208:209] op_sel_hi:[0,1]
	v_pk_add_f32 v[2:3], v[0:1], v[202:203] op_sel_hi:[0,1]
	s_waitcnt lgkmcnt(2)
	v_mfma_f32_32x32x16_bf16 v[16:31], v[4:7], v[148:151], v[16:31]
	v_add_f32_e64 v6, v0, v206
	v_add_f32_e64 v7, v0, v207
	v_add_f32_e64 v4, v0, v204
	v_add_f32_e64 v5, v0, v205
	v_pk_add_f32 v[0:1], v[0:1], v[90:91] op_sel_hi:[0,1]
	s_cselect_b64 vcc, -1, 0
	s_waitcnt lgkmcnt(1)
	v_mfma_f32_32x32x16_bf16 v[0:15], v[64:67], v[190:193], v[0:15]
	s_waitcnt lgkmcnt(0)
	v_mfma_f32_32x32x16_bf16 v[0:15], v[68:71], v[156:159], v[0:15]
	ds_read_b128 v[64:67], v178 offset:64
	ds_read_b128 v[68:71], v178 offset:96
	ds_read_b128 v[194:197], v179
	ds_read_b128 v[198:201], v179 offset:32
	s_waitcnt lgkmcnt(3)
	v_mfma_f32_32x32x16_bf16 v[0:15], v[64:67], v[152:155], v[0:15]
	v_mul_f32_e32 v64, 0x43000000, v72
	v_cndmask_b32_e32 v64, v187, v64, vcc
	v_add_f32_e64 v78, v64, v78
	v_add_f32_e64 v79, v64, v79
	v_add_f32_e64 v76, v64, v76
	v_add_f32_e64 v77, v64, v77
	v_pk_add_f32 v[74:75], v[64:65], v[74:75] op_sel_hi:[0,1]
	v_pk_add_f32 v[72:73], v[64:65], v[208:209] op_sel_hi:[0,1]
	v_pk_add_f32 v[66:67], v[64:65], v[202:203] op_sel_hi:[0,1]
	s_waitcnt lgkmcnt(2)
	v_mfma_f32_32x32x16_bf16 v[0:15], v[68:71], v[148:151], v[0:15]
	v_add_f32_e64 v70, v64, v206
	v_add_f32_e64 v71, v64, v207
	v_add_f32_e64 v68, v64, v204
	v_add_f32_e64 v69, v64, v205
	v_pk_add_f32 v[64:65], v[64:65], v[90:91] op_sel_hi:[0,1]
	s_waitcnt lgkmcnt(1)
	s_nop 0
	v_mfma_f32_32x32x16_bf16 v[64:79], v[194:197], v[190:193], v[64:79]
	s_waitcnt lgkmcnt(0)
	v_mfma_f32_32x32x16_bf16 v[64:79], v[198:201], v[156:159], v[64:79]
	ds_read_b128 v[156:159], v179 offset:64
	ds_read_b128 v[190:193], v179 offset:96
	s_waitcnt lgkmcnt(1)
	v_mfma_f32_32x32x16_bf16 v[64:79], v[156:159], v[152:155], v[64:79]
	s_waitcnt lgkmcnt(0)
	v_mfma_f32_32x32x16_bf16 v[64:79], v[190:193], v[148:151], v[64:79]
	s_movk_i32 s0, 0x81
	v_cmp_gt_i32_e32 vcc, s0, v189
	s_movk_i32 s0, 0x7f
	v_cmp_lt_i32_e64 s[0:1], s0, v189
	v_cndmask_b32_e32 v48, v187, v48, vcc
	s_nop 6
	v_cndmask_b32_e32 v153, v65, v187, vcc
	v_cndmask_b32_e64 v152, v187, v64, s[0:1]
	s_movk_i32 s0, 0x82
	v_cmp_gt_i32_e64 s[0:1], s0, v189
	v_cmp_gt_i32_e32 vcc, s65, v189
	s_nop 0
	v_cndmask_b32_e64 v49, v187, v49, s[0:1]
	v_cndmask_b32_e64 v150, v66, v187, s[0:1]
	v_cmp_gt_i32_e64 s[0:1], s66, v189
	v_cndmask_b32_e32 v50, v187, v50, vcc
	v_cndmask_b32_e32 v151, v67, v187, vcc
	v_cndmask_b32_e64 v51, v187, v51, s[0:1]
	v_cmp_lt_i32_e64 s[0:1], s68, v189
	v_cmp_gt_i32_e32 vcc, s67, v189
	s_nop 0
	v_cndmask_b32_e64 v148, v187, v68, s[0:1]
	v_cmp_gt_i32_e64 s[0:1], s69, v189
	v_cndmask_b32_e32 v52, v187, v52, vcc
	v_cndmask_b32_e32 v149, v69, v187, vcc
	v_cndmask_b32_e64 v53, v187, v53, s[0:1]
	v_cndmask_b32_e64 v90, v70, v187, s[0:1]
	v_cmp_gt_i32_e64 s[0:1], s71, v189
	v_cmp_gt_i32_e32 vcc, s70, v189
	s_nop 0
	v_cndmask_b32_e64 v55, v187, v55, s[0:1]
	v_cmp_lt_i32_e64 s[0:1], s73, v189
	v_cndmask_b32_e32 v54, v187, v54, vcc
	v_cndmask_b32_e32 v91, v71, v187, vcc
	v_cndmask_b32_e64 v72, v187, v72, s[0:1]
	v_cmp_gt_i32_e64 s[0:1], s74, v189
	v_cmp_gt_i32_e32 vcc, s72, v189
	s_nop 0
	v_cndmask_b32_e64 v57, v187, v57, s[0:1]
	v_cndmask_b32_e64 v70, v74, v187, s[0:1]
	v_cmp_gt_i32_e64 s[0:1], s76, v189
	v_cndmask_b32_e32 v56, v187, v56, vcc
	v_cndmask_b32_e32 v73, v73, v187, vcc
	v_cndmask_b32_e64 v59, v187, v59, s[0:1]
	v_cmp_lt_i32_e64 s[0:1], s82, v189
	v_cmp_gt_i32_e32 vcc, s75, v189
	s_nop 0
	v_cndmask_b32_e64 v68, v187, v76, s[0:1]
	v_cmp_gt_i32_e64 s[0:1], s83, v189
	v_cndmask_b32_e32 v58, v187, v58, vcc
	v_cndmask_b32_e32 v71, v75, v187, vcc
	v_cndmask_b32_e64 v61, v187, v61, s[0:1]
	v_cndmask_b32_e64 v66, v78, v187, s[0:1]
	v_cmp_gt_i32_e64 s[0:1], s85, v189
	v_cmp_gt_i32_e32 vcc, s77, v189
	s_nop 0
	v_cndmask_b32_e64 v63, v187, v63, s[0:1]
	s_mov_b32 s0, 0xff800000
	v_max3_f32 v64, v48, s0, v49
	v_max3_f32 v64, v64, v50, v51
	v_max3_f32 v64, v64, v52, v53
	v_max3_f32 v64, v64, v54, v55
	v_max3_f32 v64, v64, v56, v57
	v_cndmask_b32_e32 v60, v187, v60, vcc
	v_cndmask_b32_e32 v69, v77, v187, vcc
	v_cmp_gt_i32_e32 vcc, s84, v189
	v_max3_f32 v64, v64, v58, v59
	v_max3_f32 v64, v64, v60, v61
	v_cndmask_b32_e32 v62, v187, v62, vcc
	v_max3_f32 v64, v64, v62, v63
	v_max3_f32 v64, v64, v32, v33
	v_max3_f32 v64, v64, v34, v35
	v_max3_f32 v64, v64, v36, v37
	v_max3_f32 v64, v64, v38, v39
	v_max3_f32 v64, v64, v40, v41
	v_max3_f32 v64, v64, v42, v43
	v_max3_f32 v64, v64, v44, v45
	v_max3_f32 v64, v64, v46, v47
	v_max3_f32 v64, v64, v16, v17
	v_max3_f32 v64, v64, v18, v19
	v_max3_f32 v64, v64, v20, v21
	v_max3_f32 v64, v64, v22, v23
	v_max3_f32 v64, v64, v24, v25
	v_max3_f32 v64, v64, v26, v27
	v_max3_f32 v64, v64, v28, v29
	v_max3_f32 v64, v64, v30, v31
	v_max3_f32 v64, v64, v0, v1
	v_max3_f32 v64, v64, v2, v3
	v_max3_f32 v64, v64, v4, v5
	v_max3_f32 v64, v64, v6, v7
	v_max3_f32 v64, v64, v8, v9
	v_max3_f32 v64, v64, v10, v11
	v_max3_f32 v64, v64, v12, v13
	v_max3_f32 v64, v64, v14, v15
	v_max3_f32 v64, v64, v152, v153
	v_max3_f32 v64, v64, v150, v151
	v_max3_f32 v64, v64, v148, v149
	v_max3_f32 v64, v64, v90, v91
	v_max3_f32 v64, v64, v72, v73
	v_max3_f32 v64, v64, v70, v71
	v_cndmask_b32_e32 v67, v79, v187, vcc
	v_max3_f32 v64, v64, v68, v69
	v_max3_f32 v64, v64, v66, v67
	v_and_b32_e32 v74, 64, v181
	v_xor_b32_e32 v65, 32, v181
	v_add_u32_e32 v74, 64, v74
	v_cmp_lt_i32_e32 vcc, v65, v74
	s_nop 1
	v_cndmask_b32_e32 v65, v181, v65, vcc
	v_lshlrev_b32_e32 v65, 2, v65
	ds_bpermute_b32 v74, v65, v64
	s_waitcnt lgkmcnt(0)
	v_max_f32_e32 v74, v74, v74
	v_max_f32_e32 v64, v64, v74
	v_pk_add_f32 v[48:49], v[48:49], v[64:65] op_sel_hi:[1,0] neg_lo:[0,1] neg_hi:[0,1]
	v_pk_add_f32 v[50:51], v[50:51], v[64:65] op_sel_hi:[1,0] neg_lo:[0,1] neg_hi:[0,1]
	v_exp_f32_e32 v48, v48
	v_exp_f32_e32 v49, v49
	v_exp_f32_e32 v50, v50
	v_exp_f32_e32 v51, v51
	v_pk_add_f32 v[52:53], v[52:53], v[64:65] op_sel_hi:[1,0] neg_lo:[0,1] neg_hi:[0,1]
	v_pk_add_f32 v[54:55], v[54:55], v[64:65] op_sel_hi:[1,0] neg_lo:[0,1] neg_hi:[0,1]
	v_exp_f32_e32 v52, v52
	v_exp_f32_e32 v53, v53
	v_exp_f32_e32 v54, v54
	v_exp_f32_e32 v55, v55
	v_pk_add_f32 v[56:57], v[56:57], v[64:65] op_sel_hi:[1,0] neg_lo:[0,1] neg_hi:[0,1]
	v_pk_add_f32 v[74:75], v[48:49], 0 op_sel_hi:[1,0]
	v_exp_f32_e32 v56, v56
	v_exp_f32_e32 v57, v57
	v_pk_add_f32 v[74:75], v[50:51], v[74:75]
	v_cvt_pk_bf16_f32 v48, v48, v49
	v_cvt_pk_bf16_f32 v49, v50, v51
	v_cvt_pk_bf16_f32 v50, v52, v53
	v_pk_add_f32 v[58:59], v[58:59], v[64:65] op_sel_hi:[1,0] neg_lo:[0,1] neg_hi:[0,1]
	v_pk_add_f32 v[74:75], v[52:53], v[74:75]
	v_exp_f32_e32 v58, v58
	v_pk_add_f32 v[52:53], v[54:55], v[74:75]
	v_exp_f32_e32 v59, v59
	v_cvt_pk_bf16_f32 v51, v54, v55
	v_pk_add_f32 v[54:55], v[56:57], v[52:53]
	v_cvt_pk_bf16_f32 v52, v56, v57
	v_pk_add_f32 v[56:57], v[60:61], v[64:65] op_sel_hi:[1,0] neg_lo:[0,1] neg_hi:[0,1]
	v_pk_add_f32 v[60:61], v[62:63], v[64:65] op_sel_hi:[1,0] neg_lo:[0,1] neg_hi:[0,1]
	v_exp_f32_e32 v56, v56
	v_exp_f32_e32 v57, v57
	v_exp_f32_e32 v60, v60
	v_exp_f32_e32 v61, v61
	v_pk_add_f32 v[54:55], v[58:59], v[54:55]
	v_cvt_pk_bf16_f32 v53, v58, v59
	s_nop 0
	v_pk_add_f32 v[58:59], v[56:57], v[54:55]
	v_cvt_pk_bf16_f32 v54, v56, v57
	v_cvt_pk_bf16_f32 v55, v60, v61
	s_nop 0
	v_pk_add_f32 v[56:57], v[60:61], v[58:59]
	v_pk_add_f32 v[32:33], v[32:33], v[64:65] op_sel_hi:[1,0] neg_lo:[0,1] neg_hi:[0,1]
	v_pk_add_f32 v[34:35], v[34:35], v[64:65] op_sel_hi:[1,0] neg_lo:[0,1] neg_hi:[0,1]
	v_exp_f32_e32 v32, v32
	v_exp_f32_e32 v33, v33
	v_exp_f32_e32 v34, v34
	v_exp_f32_e32 v35, v35
	v_pk_add_f32 v[36:37], v[36:37], v[64:65] op_sel_hi:[1,0] neg_lo:[0,1] neg_hi:[0,1]
	v_pk_add_f32 v[38:39], v[38:39], v[64:65] op_sel_hi:[1,0] neg_lo:[0,1] neg_hi:[0,1]
	v_exp_f32_e32 v36, v36
	v_exp_f32_e32 v37, v37
	v_exp_f32_e32 v38, v38
	v_exp_f32_e32 v39, v39
	v_pk_add_f32 v[40:41], v[40:41], v[64:65] op_sel_hi:[1,0] neg_lo:[0,1] neg_hi:[0,1]
	v_pk_add_f32 v[56:57], v[32:33], v[56:57]
	v_exp_f32_e32 v40, v40
	v_exp_f32_e32 v41, v41
	v_pk_add_f32 v[56:57], v[34:35], v[56:57]
	v_cvt_pk_bf16_f32 v32, v32, v33
	v_cvt_pk_bf16_f32 v33, v34, v35
	v_cvt_pk_bf16_f32 v34, v36, v37
	v_pk_add_f32 v[42:43], v[42:43], v[64:65] op_sel_hi:[1,0] neg_lo:[0,1] neg_hi:[0,1]
	v_pk_add_f32 v[56:57], v[36:37], v[56:57]
	v_exp_f32_e32 v42, v42
	v_pk_add_f32 v[36:37], v[38:39], v[56:57]
	v_exp_f32_e32 v43, v43
	v_cvt_pk_bf16_f32 v35, v38, v39
	v_pk_add_f32 v[38:39], v[40:41], v[36:37]
	v_cvt_pk_bf16_f32 v36, v40, v41
	v_pk_add_f32 v[40:41], v[44:45], v[64:65] op_sel_hi:[1,0] neg_lo:[0,1] neg_hi:[0,1]
	v_pk_add_f32 v[44:45], v[46:47], v[64:65] op_sel_hi:[1,0] neg_lo:[0,1] neg_hi:[0,1]
	v_exp_f32_e32 v40, v40
	v_exp_f32_e32 v41, v41
	v_exp_f32_e32 v44, v44
	v_exp_f32_e32 v45, v45
	v_pk_add_f32 v[38:39], v[42:43], v[38:39]
	v_cvt_pk_bf16_f32 v37, v42, v43
	s_nop 0
	v_pk_add_f32 v[42:43], v[40:41], v[38:39]
	v_cvt_pk_bf16_f32 v38, v40, v41
	v_cvt_pk_bf16_f32 v39, v44, v45
	s_nop 0
	v_pk_add_f32 v[40:41], v[44:45], v[42:43]
	v_pk_add_f32 v[16:17], v[16:17], v[64:65] op_sel_hi:[1,0] neg_lo:[0,1] neg_hi:[0,1]
	v_pk_add_f32 v[18:19], v[18:19], v[64:65] op_sel_hi:[1,0] neg_lo:[0,1] neg_hi:[0,1]
	v_exp_f32_e32 v16, v16
	v_exp_f32_e32 v17, v17
	v_exp_f32_e32 v18, v18
	v_exp_f32_e32 v19, v19
	v_pk_add_f32 v[20:21], v[20:21], v[64:65] op_sel_hi:[1,0] neg_lo:[0,1] neg_hi:[0,1]
	v_pk_add_f32 v[42:43], v[16:17], v[40:41]
	v_exp_f32_e32 v20, v20
	v_exp_f32_e32 v21, v21
	v_pk_add_f32 v[22:23], v[22:23], v[64:65] op_sel_hi:[1,0] neg_lo:[0,1] neg_hi:[0,1]
	v_cvt_pk_bf16_f32 v40, v16, v17
	v_pk_add_f32 v[16:17], v[18:19], v[42:43]
	v_exp_f32_e32 v22, v22
	v_exp_f32_e32 v23, v23
	v_cvt_pk_bf16_f32 v41, v18, v19
	v_pk_add_f32 v[18:19], v[24:25], v[64:65] op_sel_hi:[1,0] neg_lo:[0,1] neg_hi:[0,1]
	v_pk_add_f32 v[16:17], v[20:21], v[16:17]
	v_exp_f32_e32 v18, v18
	v_exp_f32_e32 v19, v19
	v_cvt_pk_bf16_f32 v42, v20, v21
	v_pk_add_f32 v[16:17], v[22:23], v[16:17]
	v_pk_add_f32 v[20:21], v[26:27], v[64:65] op_sel_hi:[1,0] neg_lo:[0,1] neg_hi:[0,1]
	v_cvt_pk_bf16_f32 v43, v22, v23
	v_pk_add_f32 v[16:17], v[18:19], v[16:17]
	v_exp_f32_e32 v20, v20
	v_exp_f32_e32 v21, v21
	v_cvt_pk_bf16_f32 v44, v18, v19
	v_pk_add_f32 v[18:19], v[28:29], v[64:65] op_sel_hi:[1,0] neg_lo:[0,1] neg_hi:[0,1]
	v_pk_add_f32 v[22:23], v[30:31], v[64:65] op_sel_hi:[1,0] neg_lo:[0,1] neg_hi:[0,1]
	v_exp_f32_e32 v18, v18
	v_exp_f32_e32 v19, v19
	v_exp_f32_e32 v22, v22
	v_exp_f32_e32 v23, v23
	v_pk_add_f32 v[16:17], v[20:21], v[16:17]
	v_cvt_pk_bf16_f32 v45, v20, v21
	v_cvt_pk_bf16_f32 v46, v18, v19
	v_cvt_pk_bf16_f32 v47, v22, v23
	s_nop 0
	v_pk_add_f32 v[16:17], v[18:19], v[16:17]
	s_nop 0
	v_pk_add_f32 v[16:17], v[22:23], v[16:17]
	v_pk_add_f32 v[0:1], v[0:1], v[64:65] op_sel_hi:[1,0] neg_lo:[0,1] neg_hi:[0,1]
	v_pk_add_f32 v[2:3], v[2:3], v[64:65] op_sel_hi:[1,0] neg_lo:[0,1] neg_hi:[0,1]
	v_exp_f32_e32 v0, v0
	v_exp_f32_e32 v1, v1
	v_exp_f32_e32 v2, v2
	v_exp_f32_e32 v3, v3
	v_pk_add_f32 v[4:5], v[4:5], v[64:65] op_sel_hi:[1,0] neg_lo:[0,1] neg_hi:[0,1]
	v_pk_add_f32 v[16:17], v[0:1], v[16:17]
	v_exp_f32_e32 v4, v4
	v_exp_f32_e32 v5, v5
	v_pk_add_f32 v[6:7], v[6:7], v[64:65] op_sel_hi:[1,0] neg_lo:[0,1] neg_hi:[0,1]
	v_cvt_pk_bf16_f32 v56, v0, v1
	v_pk_add_f32 v[0:1], v[2:3], v[16:17]
	v_exp_f32_e32 v6, v6
	v_exp_f32_e32 v7, v7
	v_cvt_pk_bf16_f32 v57, v2, v3
	v_pk_add_f32 v[2:3], v[8:9], v[64:65] op_sel_hi:[1,0] neg_lo:[0,1] neg_hi:[0,1]
	v_pk_add_f32 v[0:1], v[4:5], v[0:1]
	v_exp_f32_e32 v2, v2
	v_exp_f32_e32 v3, v3
	v_cvt_pk_bf16_f32 v58, v4, v5
	v_pk_add_f32 v[0:1], v[6:7], v[0:1]
	v_pk_add_f32 v[4:5], v[10:11], v[64:65] op_sel_hi:[1,0] neg_lo:[0,1] neg_hi:[0,1]
	v_cvt_pk_bf16_f32 v59, v6, v7
	v_pk_add_f32 v[0:1], v[2:3], v[0:1]
	v_exp_f32_e32 v4, v4
	v_exp_f32_e32 v5, v5
	v_cvt_pk_bf16_f32 v60, v2, v3
	v_pk_add_f32 v[2:3], v[12:13], v[64:65] op_sel_hi:[1,0] neg_lo:[0,1] neg_hi:[0,1]
	v_pk_add_f32 v[6:7], v[14:15], v[64:65] op_sel_hi:[1,0] neg_lo:[0,1] neg_hi:[0,1]
	v_exp_f32_e32 v2, v2
	v_exp_f32_e32 v3, v3
	v_exp_f32_e32 v6, v6
	v_exp_f32_e32 v7, v7
	v_pk_add_f32 v[0:1], v[4:5], v[0:1]
	v_cvt_pk_bf16_f32 v61, v4, v5
	v_cvt_pk_bf16_f32 v62, v2, v3
	v_cvt_pk_bf16_f32 v63, v6, v7
	s_nop 0
	v_pk_add_f32 v[0:1], v[2:3], v[0:1]
	s_nop 0
	v_pk_add_f32 v[0:1], v[6:7], v[0:1]
	v_pk_add_f32 v[2:3], v[152:153], v[64:65] op_sel_hi:[1,0] neg_lo:[0,1] neg_hi:[0,1]
	v_pk_add_f32 v[4:5], v[150:151], v[64:65] op_sel_hi:[1,0] neg_lo:[0,1] neg_hi:[0,1]
	v_exp_f32_e32 v2, v2
	v_exp_f32_e32 v3, v3
	v_exp_f32_e32 v4, v4
	v_exp_f32_e32 v5, v5
	v_cvt_pk_bf16_f32 v74, v2, v3
	v_pk_add_f32 v[0:1], v[2:3], v[0:1]
	v_pk_add_f32 v[2:3], v[148:149], v[64:65] op_sel_hi:[1,0] neg_lo:[0,1] neg_hi:[0,1]
	v_pk_add_f32 v[0:1], v[4:5], v[0:1]
	v_exp_f32_e32 v2, v2
	v_exp_f32_e32 v3, v3
	v_pk_add_f32 v[6:7], v[90:91], v[64:65] op_sel_hi:[1,0] neg_lo:[0,1] neg_hi:[0,1]
	v_cvt_pk_bf16_f32 v75, v4, v5
	v_cvt_pk_bf16_f32 v76, v2, v3
	v_pk_add_f32 v[0:1], v[2:3], v[0:1]
	v_exp_f32_e32 v6, v6
	v_exp_f32_e32 v7, v7
	v_pk_add_f32 v[2:3], v[72:73], v[64:65] op_sel_hi:[1,0] neg_lo:[0,1] neg_hi:[0,1]
	v_pk_add_f32 v[4:5], v[70:71], v[64:65] op_sel_hi:[1,0] neg_lo:[0,1] neg_hi:[0,1]
	v_exp_f32_e32 v2, v2
	v_exp_f32_e32 v3, v3
	v_pk_add_f32 v[0:1], v[6:7], v[0:1]
	v_exp_f32_e32 v4, v4
	v_exp_f32_e32 v5, v5
	v_cvt_pk_bf16_f32 v77, v6, v7
	v_pk_add_f32 v[0:1], v[2:3], v[0:1]
	v_cvt_pk_bf16_f32 v70, v2, v3
	v_pk_add_f32 v[2:3], v[68:69], v[64:65] op_sel_hi:[1,0] neg_lo:[0,1] neg_hi:[0,1]
	v_pk_add_f32 v[6:7], v[66:67], v[64:65] op_sel_hi:[1,0] neg_lo:[0,1] neg_hi:[0,1]
	v_exp_f32_e32 v2, v2
	v_exp_f32_e32 v3, v3
	v_exp_f32_e32 v6, v6
	v_exp_f32_e32 v7, v7
	v_pk_add_f32 v[0:1], v[4:5], v[0:1]
	v_cvt_pk_bf16_f32 v71, v4, v5
	v_cvt_pk_bf16_f32 v72, v2, v3
	v_cvt_pk_bf16_f32 v73, v6, v7
	s_nop 0
	v_pk_add_f32 v[0:1], v[2:3], v[0:1]
	s_nop 0
	v_pk_add_f32 v[78:79], v[6:7], v[0:1]
	ds_read_b64_tr_b16 v[0:1], v169 offset:55296
	ds_read_b64_tr_b16 v[2:3], v169 offset:56448
	ds_read_b64_tr_b16 v[18:19], v169 offset:56512
	ds_read_b64_tr_b16 v[16:17], v169 offset:55360
	s_waitcnt lgkmcnt(2)
	v_mfma_f32_32x32x16_bf16 v[0:15], v[48:51], v[0:3], 0
	s_waitcnt lgkmcnt(0)
	v_mfma_f32_32x32x16_bf16 v[16:31], v[48:51], v[16:19], 0
	ds_read_b64_tr_b16 v[48:49], v169 offset:57600
	ds_read_b64_tr_b16 v[50:51], v169 offset:58752
	ds_read_b64_tr_b16 v[68:69], v169 offset:58816
	ds_read_b64_tr_b16 v[66:67], v169 offset:57664
	s_waitcnt lgkmcnt(2)
	v_mfma_f32_32x32x16_bf16 v[0:15], v[52:55], v[48:51], v[0:15]
	s_waitcnt lgkmcnt(0)
	v_mfma_f32_32x32x16_bf16 v[16:31], v[52:55], v[66:69], v[16:31]
	ds_read_b64_tr_b16 v[48:49], v169 offset:59904
	ds_read_b64_tr_b16 v[50:51], v169 offset:61056
	ds_read_b64_tr_b16 v[54:55], v169 offset:61120
	ds_read_b64_tr_b16 v[52:53], v169 offset:59968
	s_waitcnt lgkmcnt(2)
	v_mfma_f32_32x32x16_bf16 v[0:15], v[32:35], v[48:51], v[0:15]
	s_waitcnt lgkmcnt(0)
	v_mfma_f32_32x32x16_bf16 v[16:31], v[32:35], v[52:55], v[16:31]
	ds_read_b64_tr_b16 v[32:33], v169 offset:62208
	ds_read_b64_tr_b16 v[34:35], v169 offset:63360
	ds_read_b64_tr_b16 v[50:51], v169 offset:63424
	ds_read_b64_tr_b16 v[48:49], v169 offset:62272
	s_waitcnt lgkmcnt(2)
	v_mfma_f32_32x32x16_bf16 v[0:15], v[36:39], v[32:35], v[0:15]
	s_waitcnt lgkmcnt(0)
	v_mfma_f32_32x32x16_bf16 v[16:31], v[36:39], v[48:51], v[16:31]
	ds_read_b64_tr_b16 v[32:33], v169 offset:64512
	ds_read_b64_tr_b16 v[34:35], v170 offset:10368
	ds_read_b64_tr_b16 v[38:39], v170 offset:10432
	ds_read_b64_tr_b16 v[36:37], v169 offset:64576
	s_waitcnt lgkmcnt(2)
	v_mfma_f32_32x32x16_bf16 v[0:15], v[40:43], v[32:35], v[0:15]
	s_waitcnt lgkmcnt(0)
	v_mfma_f32_32x32x16_bf16 v[16:31], v[40:43], v[36:39], v[16:31]
	ds_read_b64_tr_b16 v[32:33], v170 offset:11520
	ds_read_b64_tr_b16 v[34:35], v170 offset:12672
	ds_read_b64_tr_b16 v[38:39], v170 offset:12736
	ds_read_b64_tr_b16 v[36:37], v170 offset:11584
	s_waitcnt lgkmcnt(2)
	v_mfma_f32_32x32x16_bf16 v[0:15], v[44:47], v[32:35], v[0:15]
	s_waitcnt lgkmcnt(0)
	v_mfma_f32_32x32x16_bf16 v[16:31], v[44:47], v[36:39], v[16:31]
	ds_read_b64_tr_b16 v[32:33], v170 offset:13824
	ds_read_b64_tr_b16 v[34:35], v170 offset:14976
	ds_read_b64_tr_b16 v[38:39], v170 offset:15040
	ds_read_b64_tr_b16 v[36:37], v170 offset:13888
	s_waitcnt lgkmcnt(2)
	v_mfma_f32_32x32x16_bf16 v[0:15], v[56:59], v[32:35], v[0:15]
	s_waitcnt lgkmcnt(0)
	v_mfma_f32_32x32x16_bf16 v[16:31], v[56:59], v[36:39], v[16:31]
	ds_read_b64_tr_b16 v[32:33], v170 offset:16128
	ds_read_b64_tr_b16 v[34:35], v170 offset:17280
	ds_read_b64_tr_b16 v[38:39], v170 offset:17344
	ds_read_b64_tr_b16 v[36:37], v170 offset:16192
	s_waitcnt lgkmcnt(2)
	v_mfma_f32_32x32x16_bf16 v[0:15], v[60:63], v[32:35], v[0:15]
	s_waitcnt lgkmcnt(0)
	v_mfma_f32_32x32x16_bf16 v[16:31], v[60:63], v[36:39], v[16:31]
	ds_read_b64_tr_b16 v[32:33], v170 offset:18432
	ds_read_b64_tr_b16 v[34:35], v170 offset:19584
	ds_read_b64_tr_b16 v[38:39], v170 offset:19648
	ds_read_b64_tr_b16 v[36:37], v170 offset:18496
	s_waitcnt lgkmcnt(2)
	v_mfma_f32_32x32x16_bf16 v[0:15], v[74:77], v[32:35], v[0:15]
	s_waitcnt lgkmcnt(0)
	v_mfma_f32_32x32x16_bf16 v[16:31], v[74:77], v[36:39], v[16:31]
	ds_read_b64_tr_b16 v[32:33], v170 offset:20736
	ds_read_b64_tr_b16 v[34:35], v170 offset:21888
	ds_read_b64_tr_b16 v[38:39], v170 offset:21952
	ds_read_b64_tr_b16 v[36:37], v170 offset:20800
	s_waitcnt lgkmcnt(2)
	v_mfma_f32_32x32x16_bf16 v[0:15], v[70:73], v[32:35], v[0:15]
	v_add_f32_e32 v32, v78, v79
	ds_bpermute_b32 v33, v65, v32
	s_waitcnt lgkmcnt(1)
	v_mfma_f32_32x32x16_bf16 v[16:31], v[70:73], v[36:39], v[16:31]
	s_and_saveexec_b64 s[0:1], s[4:5]
	s_cbranch_execz .LBB0_453
	s_waitcnt lgkmcnt(0)
	v_add_f32_e32 v34, v32, v33
	v_div_scale_f32 v36, s[18:19], v34, v34, 1.0
	v_rcp_f32_e32 v37, v36
	v_log_f32_e32 v35, v34
	s_cmp_eq_u32 s64, 0
	s_cselect_b32 s7, s86, 0x1b000000
	v_fma_f32 v38, -v36, v37, 1.0
	v_fmac_f32_e32 v37, v38, v37
	v_div_scale_f32 v38, vcc, 1.0, v34, 1.0
	v_mul_f32_e32 v39, v38, v37
	v_fma_f32 v40, -v36, v39, v38
	v_fmac_f32_e32 v39, v40, v37
	v_fma_f32 v36, -v36, v39, v38
	v_div_fmas_f32 v36, v36, v37, v39
	v_div_fixup_f32 v34, v36, v34, 1.0
	ds_write_b32 v184, v34 offset:4608
	v_rcp_f32_e32 v34, v188
	s_add_u32 s7, s40, s7
	s_addc_u32 s79, s41, 0
	s_lshl_b64 s[18:19], s[16:17], 4
	v_mul_f32_e32 v34, 0x45800000, v34
	s_or_b32 s18, s18, s63
	v_trunc_f32_e32 v34, v34
	s_mul_i32 s19, s19, s60
	s_mul_hi_u32 s95, s18, s60
	v_cvt_u32_f32_e32 v36, v34
	s_add_i32 s95, s95, s19
	s_mul_i32 s18, s18, s60
	s_add_u32 s96, s18, s61
	v_fma_f32 v34, -v34, v188, s87
	s_addc_u32 s95, s95, 0
	v_cmp_ge_f32_e64 s[18:19], |v34|, v188
	v_readfirstlane_b32 s97, v36
	s_cmp_lg_u64 s[18:19], 0
	s_addc_u32 s18, s97, 0
	s_and_b32 s18, s18, 0x1fff
	s_mul_i32 s95, s95, s18
	s_mul_hi_u32 s19, s96, s18
	s_add_i32 s19, s19, s95
	s_mul_i32 s18, s96, s18
	s_lshl_b64 s[18:19], s[18:19], 2
	v_or_b32_e32 v32, s6, v163
	s_add_u32 s18, s7, s18
	v_ashrrev_i32_e32 v33, 31, v32
	s_addc_u32 s19, s79, s19
	v_add_f32_e32 v35, v64, v35
	v_lshl_add_u64 v[32:33], v[32:33], 2, s[18:19]
	global_store_dword v[32:33], v35, off
	s_branch .LBB0_453

.LBB0_523:
	s_add_i32 s1, s62, 1
	v_cvt_f32_u32_e32 v4, s1
	v_add_u32_e32 v0, v204, v210
	s_waitcnt vmcnt(13)
	ds_write_b128 v0, v[84:87]
	s_waitcnt vmcnt(12)
	ds_write_b128 v0, v[80:83] offset:55296
	ds_write_b128 v0, v[96:99] offset:9216
	ds_write_b128 v0, v[92:95] offset:64512
	s_waitcnt vmcnt(4)
	ds_write_b128 v0, v[128:131] offset:18432
	ds_write_b128 v213, v[124:127] offset:55296
	ds_write_b128 v0, v[120:123] offset:27648
	ds_write_b128 v214, v[116:119] offset:55296
	ds_write_b128 v0, v[112:115] offset:36864
	ds_write_b128 v215, v[108:111] offset:55296
	ds_write_b128 v0, v[104:107] offset:46080
	ds_write_b128 v216, v[100:103] offset:55296
	ds_write_b128 v224, v[140:143]
	s_mov_b32 s54, s0
	v_mul_f32_e32 v0, -0.5, v4
	v_cmp_gt_f32_e64 s[6:7], s69, v0
	s_and_b64 s[18:19], s[6:7], exec
	s_cselect_b32 s1, 0xffffffc0, 0
	s_add_i32 s95, s42, s95
	s_cmpk_gt_i32 s95, 0x7ff
	s_cselect_b64 s[56:57], -1, 0
	s_and_b64 vcc, exec, s[56:57]
	ds_write_b128 v224, v[144:147] offset:1152
	ds_write_b128 v224, v[132:135] offset:2304
	ds_write_b128 v224, v[136:139] offset:3456
	s_cbranch_vccnz .LBB0_530
	s_ashr_i32 s54, s95, 8
	s_bfe_u32 s97, s95, 0x40004
	s_ashr_i32 s55, s54, 31
	s_and_b32 s96, s67, 0xf00
	s_lshl_b64 s[18:19], s[54:55], 18
	s_lshl_b32 s16, s97, 21
	s_add_u32 s58, s18, s16
	s_addc_u32 s59, s19, 0
	s_cmp_lg_u32 s96, 0
	s_cselect_b64 s[60:61], -1, 0
	s_lshl_b64 s[18:19], s[58:59], 1
	s_cmp_eq_u32 s96, 0
	v_lshl_add_u64 v[0:1], v[184:185], 0, s[18:19]
	v_lshl_add_u64 v[2:3], v[186:187], 0, s[18:19]
	s_cbranch_scc1 .LBB0_527
	s_lshl_b32 s16, s96, 7
	s_add_u32 s18, s16, 0xffffc000
	s_addc_u32 s19, 0, -1
	v_lshl_add_u64 v[6:7], v[0:1], 0, s[18:19]
	v_lshl_add_u64 v[8:9], v[2:3], 0, s[18:19]
	global_load_dwordx4 v[84:87], v[6:7], off nt
	global_load_dwordx4 v[80:83], v[8:9], off nt
	s_andn2_b64 vcc, exec, s[60:61]
	s_cbranch_vccnz .LBB0_528

.LBB0_530:
	s_waitcnt lgkmcnt(0)
	s_barrier
	v_cndmask_b32_e64 v0, 0, v225, s[6:7]
	v_fmac_f32_e32 v0, -0.5, v4
	v_exp_f32_e32 v0, v0
	s_add_i32 s6, s63, s66
	s_lshl_b32 s7, s62, 7
	v_or_b32_e32 v89, s6, v181
	v_ldexp_f32 v0, v0, s1
	s_ashr_i32 s1, s0, 31
	v_mul_f32_e32 v72, 0x3fb8aa3b, v0
	v_add_u32_e32 v0, v205, v206
	v_mov_b32_e32 v228, v207
	ds_read_b128 v[160:163], v0
	ds_read_b128 v[156:159], v0 offset:32
	ds_read_b128 v[152:155], v0 offset:64
	ds_read_b128 v[148:151], v0 offset:96
	s_cmpk_gt_i32 s6, 0x7f
	v_cvt_f32_i32_e32 v0, v228
	v_mul_f32_e32 v9, 0, v72
	s_cselect_b64 vcc, -1, 0
	v_cndmask_b32_e32 v10, v226, v9, vcc
	v_mul_f32_e64 v8, -v72, v0
	v_fma_f32 v91, -v72, v0, v72
	ds_read_b128 v[0:3], v217
	ds_read_b128 v[4:7], v217 offset:32
	v_fma_f32 v90, 0, v72, v8
	v_pk_fma_f32 v[172:173], v[72:73], s[8:9], v[8:9] op_sel_hi:[0,1,0]
	v_pk_fma_f32 v[174:175], v[72:73], s[10:11], v[8:9] op_sel_hi:[0,1,0]
	v_pk_fma_f32 v[176:177], v[72:73], s[36:37], v[8:9] op_sel_hi:[0,1,0]
	v_pk_fma_f32 v[178:179], v[72:73], s[44:45], v[8:9] op_sel_hi:[0,1,0]
	v_pk_fma_f32 v[74:75], v[72:73], s[46:47], v[8:9] op_sel_hi:[0,1,0]
	v_pk_fma_f32 v[76:77], v[72:73], s[48:49], v[8:9] op_sel_hi:[0,1,0]
	v_pk_fma_f32 v[78:79], v[72:73], s[52:53], v[8:9] op_sel_hi:[0,1,0]
	v_pk_add_f32 v[62:63], v[10:11], v[78:79] op_sel_hi:[0,1]
	v_pk_add_f32 v[60:61], v[10:11], v[76:77] op_sel_hi:[0,1]
	v_pk_add_f32 v[58:59], v[10:11], v[74:75] op_sel_hi:[0,1]
	v_pk_add_f32 v[56:57], v[10:11], v[178:179] op_sel_hi:[0,1]
	v_pk_add_f32 v[54:55], v[10:11], v[176:177] op_sel_hi:[0,1]
	v_pk_add_f32 v[52:53], v[10:11], v[174:175] op_sel_hi:[0,1]
	v_pk_add_f32 v[50:51], v[10:11], v[172:173] op_sel_hi:[0,1]
	v_pk_add_f32 v[48:49], v[10:11], v[90:91] op_sel_hi:[0,1]
	s_cmpk_gt_i32 s6, 0x5f
	v_mul_f32_e32 v12, 0x42000000, v72
	s_waitcnt lgkmcnt(1)
	v_mfma_f32_32x32x16_bf16 v[48:63], v[0:3], v[160:163], v[48:63]
	s_cselect_b64 vcc, -1, 0
	v_cndmask_b32_e32 v12, v226, v12, vcc
	v_add_f32_e64 v46, v12, v78
	v_add_f32_e64 v47, v12, v79
	v_add_f32_e64 v44, v12, v76
	v_add_f32_e64 v45, v12, v77
	v_pk_add_f32 v[42:43], v[12:13], v[74:75] op_sel_hi:[0,1]
	v_pk_add_f32 v[40:41], v[12:13], v[178:179] op_sel_hi:[0,1]
	v_pk_add_f32 v[38:39], v[12:13], v[176:177] op_sel_hi:[0,1]
	s_waitcnt lgkmcnt(0)
	v_mfma_f32_32x32x16_bf16 v[48:63], v[4:7], v[156:159], v[48:63]
	ds_read_b128 v[0:3], v217 offset:64
	ds_read_b128 v[4:7], v217 offset:96
	v_add_f32_e64 v36, v12, v174
	v_add_f32_e64 v37, v12, v175
	v_add_f32_e64 v34, v12, v172
	v_add_f32_e64 v35, v12, v173
	v_pk_add_f32 v[32:33], v[12:13], v[90:91] op_sel_hi:[0,1]
	s_cmp_gt_i32 s6, 63
	v_mul_f32_e32 v12, 0x42800000, v72
	s_cselect_b64 vcc, -1, 0
	s_waitcnt lgkmcnt(1)
	v_mfma_f32_32x32x16_bf16 v[48:63], v[0:3], v[152:155], v[48:63]
	ds_read_b128 v[0:3], v218
	ds_read_b128 v[8:11], v218 offset:32
	v_cndmask_b32_e32 v12, v226, v12, vcc
	v_add_f32_e64 v30, v12, v78
	v_add_f32_e64 v31, v12, v79
	v_pk_add_f32 v[28:29], v[12:13], v[76:77] op_sel_hi:[0,1]
	v_pk_add_f32 v[26:27], v[12:13], v[74:75] op_sel_hi:[0,1]
	v_pk_add_f32 v[24:25], v[12:13], v[178:179] op_sel_hi:[0,1]
	v_pk_add_f32 v[22:23], v[12:13], v[176:177] op_sel_hi:[0,1]
	s_waitcnt lgkmcnt(1)
	v_mfma_f32_32x32x16_bf16 v[32:47], v[0:3], v[160:163], v[32:47]
	v_add_f32_e64 v20, v12, v174
	v_add_f32_e64 v21, v12, v175
	v_add_f32_e64 v18, v12, v172
	v_add_f32_e64 v19, v12, v173
	v_add_f32_e64 v16, v12, v90
	v_add_f32_e64 v17, v12, v91
	s_cmp_gt_i32 s6, 31
	s_cselect_b64 vcc, -1, 0
	s_cmp_gt_i32 s6, -1
	s_waitcnt lgkmcnt(0)
	v_mfma_f32_32x32x16_bf16 v[32:47], v[8:11], v[156:159], v[32:47]
	v_mfma_f32_32x32x16_bf16 v[48:63], v[4:7], v[148:151], v[48:63]
	ds_read_b128 v[0:3], v218 offset:64
	ds_read_b128 v[4:7], v218 offset:96
	s_waitcnt lgkmcnt(1)
	v_mfma_f32_32x32x16_bf16 v[32:47], v[0:3], v[152:155], v[32:47]
	ds_read_b128 v[0:3], v219
	ds_read_b128 v[8:11], v219 offset:32
	s_waitcnt lgkmcnt(1)
	v_mfma_f32_32x32x16_bf16 v[16:31], v[0:3], v[160:163], v[16:31]
	s_waitcnt lgkmcnt(0)
	v_mfma_f32_32x32x16_bf16 v[16:31], v[8:11], v[156:159], v[16:31]
	v_mfma_f32_32x32x16_bf16 v[32:47], v[4:7], v[148:151], v[32:47]
	ds_read_b128 v[0:3], v219 offset:64
	ds_read_b128 v[4:7], v219 offset:96
	ds_read_b128 v[64:67], v220
	ds_read_b128 v[68:71], v220 offset:32
	s_waitcnt lgkmcnt(3)
	v_mfma_f32_32x32x16_bf16 v[16:31], v[0:3], v[152:155], v[16:31]
	v_mul_f32_e32 v0, 0x42c00000, v72
	v_cndmask_b32_e32 v0, v226, v0, vcc
	v_add_f32_e64 v14, v0, v78
	v_add_f32_e64 v15, v0, v79
	v_add_f32_e64 v12, v0, v76
	v_add_f32_e64 v13, v0, v77
	v_pk_add_f32 v[10:11], v[0:1], v[74:75] op_sel_hi:[0,1]
	v_pk_add_f32 v[8:9], v[0:1], v[178:179] op_sel_hi:[0,1]
	v_pk_add_f32 v[2:3], v[0:1], v[172:173] op_sel_hi:[0,1]
	s_waitcnt lgkmcnt(2)
	v_mfma_f32_32x32x16_bf16 v[16:31], v[4:7], v[148:151], v[16:31]
	v_add_f32_e64 v6, v0, v176
	v_add_f32_e64 v7, v0, v177
	v_add_f32_e64 v4, v0, v174
	v_add_f32_e64 v5, v0, v175
	v_pk_add_f32 v[0:1], v[0:1], v[90:91] op_sel_hi:[0,1]
	s_cselect_b64 vcc, -1, 0
	s_waitcnt lgkmcnt(1)
	v_mfma_f32_32x32x16_bf16 v[0:15], v[64:67], v[160:163], v[0:15]
	s_waitcnt lgkmcnt(0)
	v_mfma_f32_32x32x16_bf16 v[0:15], v[68:71], v[156:159], v[0:15]
	ds_read_b128 v[64:67], v220 offset:64
	ds_read_b128 v[68:71], v220 offset:96
	ds_read_b128 v[164:167], v221
	ds_read_b128 v[168:171], v221 offset:32
	s_waitcnt lgkmcnt(3)
	v_mfma_f32_32x32x16_bf16 v[0:15], v[64:67], v[152:155], v[0:15]
	v_mul_f32_e32 v64, 0x43000000, v72
	v_cndmask_b32_e32 v64, v226, v64, vcc
	v_add_f32_e64 v78, v64, v78
	v_add_f32_e64 v79, v64, v79
	v_add_f32_e64 v76, v64, v76
	v_add_f32_e64 v77, v64, v77
	v_pk_add_f32 v[74:75], v[64:65], v[74:75] op_sel_hi:[0,1]
	v_pk_add_f32 v[72:73], v[64:65], v[178:179] op_sel_hi:[0,1]
	v_pk_add_f32 v[66:67], v[64:65], v[172:173] op_sel_hi:[0,1]
	s_waitcnt lgkmcnt(2)
	v_mfma_f32_32x32x16_bf16 v[0:15], v[68:71], v[148:151], v[0:15]
	v_add_f32_e64 v70, v64, v176
	v_add_f32_e64 v71, v64, v177
	v_add_f32_e64 v68, v64, v174
	v_add_f32_e64 v69, v64, v175
	v_pk_add_f32 v[64:65], v[64:65], v[90:91] op_sel_hi:[0,1]
	s_waitcnt lgkmcnt(1)
	s_nop 0
	v_mfma_f32_32x32x16_bf16 v[64:79], v[164:167], v[160:163], v[64:79]
	s_waitcnt lgkmcnt(0)
	v_mfma_f32_32x32x16_bf16 v[64:79], v[168:171], v[156:159], v[64:79]
	ds_read_b128 v[156:159], v221 offset:64
	ds_read_b128 v[160:163], v221 offset:96
	s_waitcnt lgkmcnt(1)
	v_mfma_f32_32x32x16_bf16 v[64:79], v[156:159], v[152:155], v[64:79]
	s_waitcnt lgkmcnt(0)
	v_mfma_f32_32x32x16_bf16 v[64:79], v[160:163], v[148:151], v[64:79]
	s_lshl_b64 s[18:19], s[0:1], 18
	s_lshl_b32 s16, s62, 14
	s_lshl_b64 s[64:65], s[0:1], 23
	v_ashrrev_i32_e32 v90, 2, v89
	s_or_b32 s18, s18, s16
	s_or_b32 s64, s64, s7
	s_ashr_i32 s7, s6, 31
	v_ashrrev_i32_e32 v91, 31, v90
	v_lshl_add_u64 v[148:149], v[194:195], 0, s[18:19]
	s_lshl_b64 s[62:63], s[6:7], 11
	v_lshl_add_u64 v[90:91], v[90:91], 2, v[148:149]
	v_ashrrev_i32_e32 v148, 4, v89
	s_add_u32 s0, s64, s62
	v_ashrrev_i32_e32 v149, 31, v148
	v_lshl_add_u64 v[150:151], v[196:197], 0, s[18:19]
	s_addc_u32 s1, s65, s63
	v_lshl_add_u64 v[148:149], v[148:149], 2, v[150:151]
	v_lshl_add_u64 v[150:151], v[190:191], 0, s[0:1]
	global_load_dword v227, v[90:91], off
	global_load_dword v89, v[148:149], off
	global_load_dwordx4 v[176:179], v[150:151], off
	v_lshl_add_u64 v[90:91], v[192:193], 0, s[0:1]
	s_or_b32 s0, s6, 8
	s_ashr_i32 s1, s0, 31
	s_lshl_b64 s[60:61], s[0:1], 11
	s_add_u32 s0, s64, s60
	s_addc_u32 s1, s65, s61
	global_load_dwordx4 v[172:175], v[90:91], off
	v_lshl_add_u64 v[90:91], v[190:191], 0, s[0:1]
	global_load_dwordx4 v[168:171], v[90:91], off
	v_lshl_add_u64 v[90:91], v[192:193], 0, s[0:1]
	s_or_b32 s0, s6, 16
	s_ashr_i32 s1, s0, 31
	s_lshl_b64 s[58:59], s[0:1], 11
	s_add_u32 s0, s64, s58
	s_addc_u32 s1, s65, s59
	global_load_dwordx4 v[164:167], v[90:91], off
	v_lshl_add_u64 v[90:91], v[190:191], 0, s[0:1]
	global_load_dwordx4 v[160:163], v[90:91], off
	v_lshl_add_u64 v[90:91], v[192:193], 0, s[0:1]
	s_or_b32 s0, s6, 24
	s_ashr_i32 s1, s0, 31
	s_lshl_b64 s[6:7], s[0:1], 11
	s_add_u32 s0, s64, s6
	s_addc_u32 s1, s65, s7
	global_load_dwordx4 v[156:159], v[90:91], off
	v_lshl_add_u64 v[90:91], v[190:191], 0, s[0:1]
	global_load_dwordx4 v[152:155], v[90:91], off
	v_lshl_add_u64 v[90:91], v[192:193], 0, s[0:1]
	global_load_dwordx4 v[148:151], v[90:91], off
	v_cmp_lt_i32_e64 s[0:1], s70, v228
	v_cmp_gt_i32_e32 vcc, s72, v228
	s_nop 0
	v_cndmask_b32_e64 v202, v226, v64, s[0:1]
	v_cmp_gt_i32_e64 s[0:1], s73, v228
	v_cndmask_b32_e32 v48, v226, v48, vcc
	v_cndmask_b32_e32 v203, v65, v226, vcc
	v_cndmask_b32_e64 v49, v226, v49, s[0:1]
	v_cndmask_b32_e64 v200, v66, v226, s[0:1]
	v_cmp_gt_i32_e64 s[0:1], s75, v228
	v_cmp_gt_i32_e32 vcc, s74, v228
	v_max3_f32 v64, v48, s71, v49
	v_cndmask_b32_e64 v51, v226, v51, s[0:1]
	v_cmp_lt_i32_e64 s[0:1], s77, v228
	v_cndmask_b32_e32 v50, v226, v50, vcc
	v_cndmask_b32_e32 v201, v67, v226, vcc
	v_cndmask_b32_e64 v198, v226, v68, s[0:1]
	v_cmp_gt_i32_e64 s[0:1], s82, v228
	v_cmp_gt_i32_e32 vcc, s76, v228
	v_max3_f32 v64, v64, v50, v51
	v_cndmask_b32_e64 v53, v226, v53, s[0:1]
	v_cndmask_b32_e64 v90, v70, v226, s[0:1]
	v_cmp_gt_i32_e64 s[0:1], s84, v228
	v_cndmask_b32_e32 v52, v226, v52, vcc
	v_cndmask_b32_e32 v199, v69, v226, vcc
	v_cndmask_b32_e64 v55, v226, v55, s[0:1]
	v_cmp_lt_i32_e64 s[0:1], s86, v228
	v_cmp_gt_i32_e32 vcc, s83, v228
	v_max3_f32 v64, v64, v52, v53
	v_cndmask_b32_e64 v72, v226, v72, s[0:1]
	v_cmp_gt_i32_e64 s[0:1], s87, v228
	v_cndmask_b32_e32 v54, v226, v54, vcc
	v_cndmask_b32_e32 v91, v71, v226, vcc
	v_cmp_gt_i32_e32 vcc, s85, v228
	v_cndmask_b32_e64 v57, v226, v57, s[0:1]
	v_cndmask_b32_e64 v70, v74, v226, s[0:1]
	v_cmp_gt_i32_e64 s[0:1], s89, v228
	v_cndmask_b32_e32 v56, v226, v56, vcc
	v_cndmask_b32_e32 v73, v73, v226, vcc
	v_cmp_gt_i32_e32 vcc, s88, v228
	v_cndmask_b32_e64 v59, v226, v59, s[0:1]
	v_cmp_lt_i32_e64 s[0:1], s91, v228
	v_max3_f32 v64, v64, v54, v55
	v_cndmask_b32_e32 v58, v226, v58, vcc
	v_cndmask_b32_e32 v71, v75, v226, vcc
	v_cmp_gt_i32_e32 vcc, s90, v228
	v_cndmask_b32_e64 v68, v226, v76, s[0:1]
	v_cmp_gt_i32_e64 s[0:1], s92, v228
	v_max3_f32 v64, v64, v56, v57
	v_cndmask_b32_e32 v60, v226, v60, vcc
	v_cndmask_b32_e64 v61, v226, v61, s[0:1]
	v_cndmask_b32_e32 v69, v77, v226, vcc
	v_cmp_gt_i32_e32 vcc, s93, v228
	v_cndmask_b32_e64 v66, v78, v226, s[0:1]
	v_cmp_gt_i32_e64 s[0:1], s94, v228
	v_max3_f32 v64, v64, v58, v59
	v_cndmask_b32_e32 v62, v226, v62, vcc
	v_cndmask_b32_e64 v63, v226, v63, s[0:1]
	v_max3_f32 v64, v64, v60, v61
	v_max3_f32 v64, v64, v62, v63
	v_max3_f32 v64, v64, v32, v33
	v_max3_f32 v64, v64, v34, v35
	v_max3_f32 v64, v64, v36, v37
	v_max3_f32 v64, v64, v38, v39
	v_max3_f32 v64, v64, v40, v41
	v_max3_f32 v64, v64, v42, v43
	v_max3_f32 v64, v64, v44, v45
	v_max3_f32 v64, v64, v46, v47
	v_max3_f32 v64, v64, v16, v17
	v_max3_f32 v64, v64, v18, v19
	v_max3_f32 v64, v64, v20, v21
	v_max3_f32 v64, v64, v22, v23
	v_max3_f32 v64, v64, v24, v25
	v_max3_f32 v64, v64, v26, v27
	v_max3_f32 v64, v64, v28, v29
	v_max3_f32 v64, v64, v30, v31
	v_max3_f32 v64, v64, v0, v1
	v_max3_f32 v64, v64, v2, v3
	v_max3_f32 v64, v64, v4, v5
	v_max3_f32 v64, v64, v6, v7
	v_max3_f32 v64, v64, v8, v9
	v_max3_f32 v64, v64, v10, v11
	v_max3_f32 v64, v64, v12, v13
	v_max3_f32 v64, v64, v14, v15
	v_max3_f32 v64, v64, v202, v203
	v_max3_f32 v64, v64, v200, v201
	v_max3_f32 v64, v64, v198, v199
	v_max3_f32 v64, v64, v90, v91
	v_max3_f32 v64, v64, v72, v73
	v_max3_f32 v64, v64, v70, v71
	v_cndmask_b32_e32 v67, v79, v226, vcc
	v_max3_f32 v64, v64, v68, v69
	v_max3_f32 v64, v64, v66, v67
	v_and_b32_e32 v74, 64, v222
	v_xor_b32_e32 v65, 32, v222
	v_add_u32_e32 v74, 64, v74
	v_cmp_lt_i32_e32 vcc, v65, v74
	s_nop 1
	v_cndmask_b32_e32 v65, v222, v65, vcc
	v_lshlrev_b32_e32 v65, 2, v65
	ds_bpermute_b32 v74, v65, v64
	s_waitcnt lgkmcnt(0)
	v_max_f32_e32 v74, v74, v74
	v_max_f32_e32 v64, v64, v74
	v_pk_add_f32 v[48:49], v[48:49], v[64:65] op_sel_hi:[1,0] neg_lo:[0,1] neg_hi:[0,1]
	v_pk_add_f32 v[50:51], v[50:51], v[64:65] op_sel_hi:[1,0] neg_lo:[0,1] neg_hi:[0,1]
	v_exp_f32_e32 v48, v48
	v_exp_f32_e32 v49, v49
	v_exp_f32_e32 v50, v50
	v_exp_f32_e32 v51, v51
	v_pk_add_f32 v[52:53], v[52:53], v[64:65] op_sel_hi:[1,0] neg_lo:[0,1] neg_hi:[0,1]
	v_pk_add_f32 v[54:55], v[54:55], v[64:65] op_sel_hi:[1,0] neg_lo:[0,1] neg_hi:[0,1]
	v_exp_f32_e32 v52, v52
	v_exp_f32_e32 v53, v53
	v_exp_f32_e32 v54, v54
	v_exp_f32_e32 v55, v55
	v_pk_add_f32 v[56:57], v[56:57], v[64:65] op_sel_hi:[1,0] neg_lo:[0,1] neg_hi:[0,1]
	v_pk_add_f32 v[74:75], v[48:49], 0 op_sel_hi:[1,0]
	v_exp_f32_e32 v56, v56
	v_exp_f32_e32 v57, v57
	v_pk_add_f32 v[74:75], v[50:51], v[74:75]
	v_cvt_pk_bf16_f32 v48, v48, v49
	v_cvt_pk_bf16_f32 v49, v50, v51
	v_cvt_pk_bf16_f32 v50, v52, v53
	v_pk_add_f32 v[58:59], v[58:59], v[64:65] op_sel_hi:[1,0] neg_lo:[0,1] neg_hi:[0,1]
	v_pk_add_f32 v[74:75], v[52:53], v[74:75]
	v_exp_f32_e32 v58, v58
	v_pk_add_f32 v[52:53], v[54:55], v[74:75]
	v_exp_f32_e32 v59, v59
	v_cvt_pk_bf16_f32 v51, v54, v55
	v_pk_add_f32 v[54:55], v[56:57], v[52:53]
	v_cvt_pk_bf16_f32 v52, v56, v57
	v_pk_add_f32 v[56:57], v[60:61], v[64:65] op_sel_hi:[1,0] neg_lo:[0,1] neg_hi:[0,1]
	v_pk_add_f32 v[60:61], v[62:63], v[64:65] op_sel_hi:[1,0] neg_lo:[0,1] neg_hi:[0,1]
	v_exp_f32_e32 v56, v56
	v_exp_f32_e32 v57, v57
	v_exp_f32_e32 v60, v60
	v_exp_f32_e32 v61, v61
	v_pk_add_f32 v[54:55], v[58:59], v[54:55]
	v_cvt_pk_bf16_f32 v53, v58, v59
	s_nop 0
	v_pk_add_f32 v[58:59], v[56:57], v[54:55]
	v_cvt_pk_bf16_f32 v54, v56, v57
	v_cvt_pk_bf16_f32 v55, v60, v61
	s_nop 0
	v_pk_add_f32 v[56:57], v[60:61], v[58:59]
	v_pk_add_f32 v[32:33], v[32:33], v[64:65] op_sel_hi:[1,0] neg_lo:[0,1] neg_hi:[0,1]
	v_pk_add_f32 v[34:35], v[34:35], v[64:65] op_sel_hi:[1,0] neg_lo:[0,1] neg_hi:[0,1]
	v_exp_f32_e32 v32, v32
	v_exp_f32_e32 v33, v33
	v_exp_f32_e32 v34, v34
	v_exp_f32_e32 v35, v35
	v_pk_add_f32 v[36:37], v[36:37], v[64:65] op_sel_hi:[1,0] neg_lo:[0,1] neg_hi:[0,1]
	v_pk_add_f32 v[38:39], v[38:39], v[64:65] op_sel_hi:[1,0] neg_lo:[0,1] neg_hi:[0,1]
	v_exp_f32_e32 v36, v36
	v_exp_f32_e32 v37, v37
	v_exp_f32_e32 v38, v38
	v_exp_f32_e32 v39, v39
	v_pk_add_f32 v[40:41], v[40:41], v[64:65] op_sel_hi:[1,0] neg_lo:[0,1] neg_hi:[0,1]
	v_pk_add_f32 v[56:57], v[32:33], v[56:57]
	v_exp_f32_e32 v40, v40
	v_exp_f32_e32 v41, v41
	v_pk_add_f32 v[56:57], v[34:35], v[56:57]
	v_cvt_pk_bf16_f32 v32, v32, v33
	v_cvt_pk_bf16_f32 v33, v34, v35
	v_cvt_pk_bf16_f32 v34, v36, v37
	v_pk_add_f32 v[42:43], v[42:43], v[64:65] op_sel_hi:[1,0] neg_lo:[0,1] neg_hi:[0,1]
	v_pk_add_f32 v[56:57], v[36:37], v[56:57]
	v_exp_f32_e32 v42, v42
	v_pk_add_f32 v[36:37], v[38:39], v[56:57]
	v_exp_f32_e32 v43, v43
	v_cvt_pk_bf16_f32 v35, v38, v39
	v_pk_add_f32 v[38:39], v[40:41], v[36:37]
	v_cvt_pk_bf16_f32 v36, v40, v41
	v_pk_add_f32 v[40:41], v[44:45], v[64:65] op_sel_hi:[1,0] neg_lo:[0,1] neg_hi:[0,1]
	v_pk_add_f32 v[44:45], v[46:47], v[64:65] op_sel_hi:[1,0] neg_lo:[0,1] neg_hi:[0,1]
	v_exp_f32_e32 v40, v40
	v_exp_f32_e32 v41, v41
	v_exp_f32_e32 v44, v44
	v_exp_f32_e32 v45, v45
	v_pk_add_f32 v[38:39], v[42:43], v[38:39]
	v_cvt_pk_bf16_f32 v37, v42, v43
	s_nop 0
	v_pk_add_f32 v[42:43], v[40:41], v[38:39]
	v_cvt_pk_bf16_f32 v38, v40, v41
	v_cvt_pk_bf16_f32 v39, v44, v45
	s_nop 0
	v_pk_add_f32 v[40:41], v[44:45], v[42:43]
	v_pk_add_f32 v[16:17], v[16:17], v[64:65] op_sel_hi:[1,0] neg_lo:[0,1] neg_hi:[0,1]
	v_pk_add_f32 v[18:19], v[18:19], v[64:65] op_sel_hi:[1,0] neg_lo:[0,1] neg_hi:[0,1]
	v_exp_f32_e32 v16, v16
	v_exp_f32_e32 v17, v17
	v_exp_f32_e32 v18, v18
	v_exp_f32_e32 v19, v19
	v_pk_add_f32 v[20:21], v[20:21], v[64:65] op_sel_hi:[1,0] neg_lo:[0,1] neg_hi:[0,1]
	v_pk_add_f32 v[42:43], v[16:17], v[40:41]
	v_exp_f32_e32 v20, v20
	v_exp_f32_e32 v21, v21
	v_pk_add_f32 v[22:23], v[22:23], v[64:65] op_sel_hi:[1,0] neg_lo:[0,1] neg_hi:[0,1]
	v_cvt_pk_bf16_f32 v40, v16, v17
	v_pk_add_f32 v[16:17], v[18:19], v[42:43]
	v_exp_f32_e32 v22, v22
	v_exp_f32_e32 v23, v23
	v_cvt_pk_bf16_f32 v41, v18, v19
	v_pk_add_f32 v[18:19], v[24:25], v[64:65] op_sel_hi:[1,0] neg_lo:[0,1] neg_hi:[0,1]
	v_pk_add_f32 v[16:17], v[20:21], v[16:17]
	v_exp_f32_e32 v18, v18
	v_exp_f32_e32 v19, v19
	v_cvt_pk_bf16_f32 v42, v20, v21
	v_pk_add_f32 v[16:17], v[22:23], v[16:17]
	v_pk_add_f32 v[20:21], v[26:27], v[64:65] op_sel_hi:[1,0] neg_lo:[0,1] neg_hi:[0,1]
	v_cvt_pk_bf16_f32 v43, v22, v23
	v_pk_add_f32 v[16:17], v[18:19], v[16:17]
	v_exp_f32_e32 v20, v20
	v_exp_f32_e32 v21, v21
	v_cvt_pk_bf16_f32 v44, v18, v19
	v_pk_add_f32 v[18:19], v[28:29], v[64:65] op_sel_hi:[1,0] neg_lo:[0,1] neg_hi:[0,1]
	v_pk_add_f32 v[22:23], v[30:31], v[64:65] op_sel_hi:[1,0] neg_lo:[0,1] neg_hi:[0,1]
	v_exp_f32_e32 v18, v18
	v_exp_f32_e32 v19, v19
	v_exp_f32_e32 v22, v22
	v_exp_f32_e32 v23, v23
	v_pk_add_f32 v[16:17], v[20:21], v[16:17]
	v_cvt_pk_bf16_f32 v45, v20, v21
	v_cvt_pk_bf16_f32 v46, v18, v19
	v_cvt_pk_bf16_f32 v47, v22, v23
	s_nop 0
	v_pk_add_f32 v[16:17], v[18:19], v[16:17]
	s_nop 0
	v_pk_add_f32 v[16:17], v[22:23], v[16:17]
	v_pk_add_f32 v[0:1], v[0:1], v[64:65] op_sel_hi:[1,0] neg_lo:[0,1] neg_hi:[0,1]
	v_pk_add_f32 v[2:3], v[2:3], v[64:65] op_sel_hi:[1,0] neg_lo:[0,1] neg_hi:[0,1]
	v_exp_f32_e32 v0, v0
	v_exp_f32_e32 v1, v1
	v_exp_f32_e32 v2, v2
	v_exp_f32_e32 v3, v3
	v_pk_add_f32 v[4:5], v[4:5], v[64:65] op_sel_hi:[1,0] neg_lo:[0,1] neg_hi:[0,1]
	v_pk_add_f32 v[16:17], v[0:1], v[16:17]
	v_exp_f32_e32 v4, v4
	v_exp_f32_e32 v5, v5
	v_pk_add_f32 v[6:7], v[6:7], v[64:65] op_sel_hi:[1,0] neg_lo:[0,1] neg_hi:[0,1]
	v_cvt_pk_bf16_f32 v56, v0, v1
	v_pk_add_f32 v[0:1], v[2:3], v[16:17]
	v_exp_f32_e32 v6, v6
	v_exp_f32_e32 v7, v7
	v_cvt_pk_bf16_f32 v57, v2, v3
	v_pk_add_f32 v[2:3], v[8:9], v[64:65] op_sel_hi:[1,0] neg_lo:[0,1] neg_hi:[0,1]
	v_pk_add_f32 v[0:1], v[4:5], v[0:1]
	v_exp_f32_e32 v2, v2
	v_exp_f32_e32 v3, v3
	v_cvt_pk_bf16_f32 v58, v4, v5
	v_pk_add_f32 v[0:1], v[6:7], v[0:1]
	v_pk_add_f32 v[4:5], v[10:11], v[64:65] op_sel_hi:[1,0] neg_lo:[0,1] neg_hi:[0,1]
	v_cvt_pk_bf16_f32 v59, v6, v7
	v_pk_add_f32 v[0:1], v[2:3], v[0:1]
	v_exp_f32_e32 v4, v4
	v_exp_f32_e32 v5, v5
	v_cvt_pk_bf16_f32 v60, v2, v3
	v_pk_add_f32 v[2:3], v[12:13], v[64:65] op_sel_hi:[1,0] neg_lo:[0,1] neg_hi:[0,1]
	v_pk_add_f32 v[6:7], v[14:15], v[64:65] op_sel_hi:[1,0] neg_lo:[0,1] neg_hi:[0,1]
	v_exp_f32_e32 v2, v2
	v_exp_f32_e32 v3, v3
	v_exp_f32_e32 v6, v6
	v_exp_f32_e32 v7, v7
	v_pk_add_f32 v[0:1], v[4:5], v[0:1]
	v_cvt_pk_bf16_f32 v61, v4, v5
	v_cvt_pk_bf16_f32 v62, v2, v3
	v_cvt_pk_bf16_f32 v63, v6, v7
	s_nop 0
	v_pk_add_f32 v[0:1], v[2:3], v[0:1]
	s_nop 0
	v_pk_add_f32 v[0:1], v[6:7], v[0:1]
	v_pk_add_f32 v[2:3], v[202:203], v[64:65] op_sel_hi:[1,0] neg_lo:[0,1] neg_hi:[0,1]
	v_pk_add_f32 v[4:5], v[200:201], v[64:65] op_sel_hi:[1,0] neg_lo:[0,1] neg_hi:[0,1]
	v_exp_f32_e32 v2, v2
	v_exp_f32_e32 v3, v3
	v_exp_f32_e32 v4, v4
	v_exp_f32_e32 v5, v5
	v_cvt_pk_bf16_f32 v74, v2, v3
	v_pk_add_f32 v[0:1], v[2:3], v[0:1]
	v_pk_add_f32 v[2:3], v[198:199], v[64:65] op_sel_hi:[1,0] neg_lo:[0,1] neg_hi:[0,1]
	v_pk_add_f32 v[0:1], v[4:5], v[0:1]
	v_exp_f32_e32 v2, v2
	v_exp_f32_e32 v3, v3
	v_pk_add_f32 v[6:7], v[90:91], v[64:65] op_sel_hi:[1,0] neg_lo:[0,1] neg_hi:[0,1]
	v_cvt_pk_bf16_f32 v75, v4, v5
	v_cvt_pk_bf16_f32 v76, v2, v3
	v_pk_add_f32 v[0:1], v[2:3], v[0:1]
	v_exp_f32_e32 v6, v6
	v_exp_f32_e32 v7, v7
	v_pk_add_f32 v[2:3], v[72:73], v[64:65] op_sel_hi:[1,0] neg_lo:[0,1] neg_hi:[0,1]
	v_pk_add_f32 v[4:5], v[70:71], v[64:65] op_sel_hi:[1,0] neg_lo:[0,1] neg_hi:[0,1]
	v_exp_f32_e32 v2, v2
	v_exp_f32_e32 v3, v3
	v_pk_add_f32 v[0:1], v[6:7], v[0:1]
	v_exp_f32_e32 v4, v4
	v_exp_f32_e32 v5, v5
	v_cvt_pk_bf16_f32 v77, v6, v7
	v_pk_add_f32 v[0:1], v[2:3], v[0:1]
	v_cvt_pk_bf16_f32 v70, v2, v3
	v_pk_add_f32 v[2:3], v[68:69], v[64:65] op_sel_hi:[1,0] neg_lo:[0,1] neg_hi:[0,1]
	v_pk_add_f32 v[6:7], v[66:67], v[64:65] op_sel_hi:[1,0] neg_lo:[0,1] neg_hi:[0,1]
	v_exp_f32_e32 v2, v2
	v_exp_f32_e32 v3, v3
	v_exp_f32_e32 v6, v6
	v_exp_f32_e32 v7, v7
	v_pk_add_f32 v[0:1], v[4:5], v[0:1]
	v_cvt_pk_bf16_f32 v71, v4, v5
	v_cvt_pk_bf16_f32 v72, v2, v3
	v_cvt_pk_bf16_f32 v73, v6, v7
	s_nop 0
	v_pk_add_f32 v[0:1], v[2:3], v[0:1]
	s_nop 0
	v_pk_add_f32 v[78:79], v[6:7], v[0:1]
	ds_read_b64_tr_b16 v[0:1], v208 offset:55296
	ds_read_b64_tr_b16 v[2:3], v208 offset:56448
	ds_read_b64_tr_b16 v[18:19], v208 offset:56512
	ds_read_b64_tr_b16 v[16:17], v208 offset:55360
	s_waitcnt lgkmcnt(2)
	v_mfma_f32_32x32x16_bf16 v[0:15], v[48:51], v[0:3], 0
	s_waitcnt lgkmcnt(0)
	v_mfma_f32_32x32x16_bf16 v[16:31], v[48:51], v[16:19], 0
	ds_read_b64_tr_b16 v[48:49], v208 offset:57600
	ds_read_b64_tr_b16 v[50:51], v208 offset:58752
	ds_read_b64_tr_b16 v[68:69], v208 offset:58816
	ds_read_b64_tr_b16 v[66:67], v208 offset:57664
	s_waitcnt lgkmcnt(2)
	v_mfma_f32_32x32x16_bf16 v[0:15], v[52:55], v[48:51], v[0:15]
	s_waitcnt lgkmcnt(0)
	v_mfma_f32_32x32x16_bf16 v[16:31], v[52:55], v[66:69], v[16:31]
	ds_read_b64_tr_b16 v[48:49], v208 offset:59904
	ds_read_b64_tr_b16 v[50:51], v208 offset:61056
	ds_read_b64_tr_b16 v[54:55], v208 offset:61120
	ds_read_b64_tr_b16 v[52:53], v208 offset:59968
	s_waitcnt lgkmcnt(2)
	v_mfma_f32_32x32x16_bf16 v[0:15], v[32:35], v[48:51], v[0:15]
	s_waitcnt lgkmcnt(0)
	v_mfma_f32_32x32x16_bf16 v[16:31], v[32:35], v[52:55], v[16:31]
	ds_read_b64_tr_b16 v[32:33], v208 offset:62208
	ds_read_b64_tr_b16 v[34:35], v208 offset:63360
	ds_read_b64_tr_b16 v[50:51], v208 offset:63424
	ds_read_b64_tr_b16 v[48:49], v208 offset:62272
	s_waitcnt lgkmcnt(2)
	v_mfma_f32_32x32x16_bf16 v[0:15], v[36:39], v[32:35], v[0:15]
	s_waitcnt lgkmcnt(0)
	v_mfma_f32_32x32x16_bf16 v[16:31], v[36:39], v[48:51], v[16:31]
	ds_read_b64_tr_b16 v[32:33], v208 offset:64512
	ds_read_b64_tr_b16 v[34:35], v209 offset:10368
	ds_read_b64_tr_b16 v[38:39], v209 offset:10432
	ds_read_b64_tr_b16 v[36:37], v208 offset:64576
	s_waitcnt lgkmcnt(2)
	v_mfma_f32_32x32x16_bf16 v[0:15], v[40:43], v[32:35], v[0:15]
	s_waitcnt lgkmcnt(0)
	v_mfma_f32_32x32x16_bf16 v[16:31], v[40:43], v[36:39], v[16:31]
	ds_read_b64_tr_b16 v[32:33], v209 offset:11520
	ds_read_b64_tr_b16 v[34:35], v209 offset:12672
	ds_read_b64_tr_b16 v[38:39], v209 offset:12736
	ds_read_b64_tr_b16 v[36:37], v209 offset:11584
	s_waitcnt lgkmcnt(2)
	v_mfma_f32_32x32x16_bf16 v[0:15], v[44:47], v[32:35], v[0:15]
	s_waitcnt lgkmcnt(0)
	v_mfma_f32_32x32x16_bf16 v[16:31], v[44:47], v[36:39], v[16:31]
	ds_read_b64_tr_b16 v[32:33], v209 offset:13824
	ds_read_b64_tr_b16 v[34:35], v209 offset:14976
	ds_read_b64_tr_b16 v[38:39], v209 offset:15040
	ds_read_b64_tr_b16 v[36:37], v209 offset:13888
	s_waitcnt lgkmcnt(2)
	v_mfma_f32_32x32x16_bf16 v[0:15], v[56:59], v[32:35], v[0:15]
	s_waitcnt lgkmcnt(0)
	v_mfma_f32_32x32x16_bf16 v[16:31], v[56:59], v[36:39], v[16:31]
	ds_read_b64_tr_b16 v[32:33], v209 offset:16128
	ds_read_b64_tr_b16 v[34:35], v209 offset:17280
	ds_read_b64_tr_b16 v[38:39], v209 offset:17344
	ds_read_b64_tr_b16 v[36:37], v209 offset:16192
	s_waitcnt lgkmcnt(2)
	v_mfma_f32_32x32x16_bf16 v[0:15], v[60:63], v[32:35], v[0:15]
	s_waitcnt lgkmcnt(0)
	v_mfma_f32_32x32x16_bf16 v[16:31], v[60:63], v[36:39], v[16:31]
	ds_read_b64_tr_b16 v[32:33], v209 offset:18432
	ds_read_b64_tr_b16 v[34:35], v209 offset:19584
	ds_read_b64_tr_b16 v[38:39], v209 offset:19648
	ds_read_b64_tr_b16 v[36:37], v209 offset:18496
	s_waitcnt lgkmcnt(2)
	v_mfma_f32_32x32x16_bf16 v[0:15], v[74:77], v[32:35], v[0:15]
	s_waitcnt lgkmcnt(0)
	v_mfma_f32_32x32x16_bf16 v[16:31], v[74:77], v[36:39], v[16:31]
	ds_read_b64_tr_b16 v[32:33], v209 offset:20736
	ds_read_b64_tr_b16 v[34:35], v209 offset:21888
	ds_read_b64_tr_b16 v[38:39], v209 offset:21952
	ds_read_b64_tr_b16 v[36:37], v209 offset:20800
	s_waitcnt lgkmcnt(2)
	v_mfma_f32_32x32x16_bf16 v[0:15], v[70:73], v[32:35], v[0:15]
	v_add_f32_e32 v32, v78, v79
	ds_bpermute_b32 v33, v65, v32
	s_waitcnt lgkmcnt(1)
	v_mfma_f32_32x32x16_bf16 v[16:31], v[70:73], v[36:39], v[16:31]
	s_and_saveexec_b64 s[0:1], s[4:5]
	s_cbranch_execz .LBB0_522
	s_waitcnt lgkmcnt(0)
	v_add_f32_e32 v32, v32, v33
	v_log_f32_e32 v33, v32
	s_nop 0
	v_add_f32_e32 v33, v64, v33
	s_waitcnt vmcnt(8)
	v_max3_f32 v34, v33, v227, v89
	v_sub_f32_e32 v33, v33, v34
	v_sub_f32_e32 v35, v227, v34
	v_sub_f32_e32 v34, v89, v34
	v_exp_f32_e32 v33, v33
	v_exp_f32_e32 v35, v35
	v_exp_f32_e32 v34, v34
	v_add_f32_e32 v36, v33, v35
	v_add_f32_e32 v36, v34, v36
	v_div_scale_f32 v37, s[18:19], v36, v36, 1.0
	v_rcp_f32_e32 v38, v37
	v_div_scale_f32 v39, vcc, 1.0, v36, 1.0
	v_fma_f32 v40, -v37, v38, 1.0
	v_fmac_f32_e32 v38, v40, v38
	v_mul_f32_e32 v40, v39, v38
	v_fma_f32 v41, -v37, v40, v39
	v_fmac_f32_e32 v40, v41, v38
	v_fma_f32 v37, -v37, v40, v39
	v_div_fmas_f32 v37, v37, v38, v40
	v_div_fixup_f32 v36, v37, v36, 1.0
	v_mul_f32_e32 v33, v33, v36
	v_div_scale_f32 v37, s[18:19], v32, v32, v33
	v_rcp_f32_e32 v38, v37
	v_div_scale_f32 v39, vcc, v33, v32, v33
	v_fma_f32 v40, -v37, v38, 1.0
	v_fmac_f32_e32 v38, v40, v38
	v_mul_f32_e32 v40, v39, v38
	v_fma_f32 v41, -v37, v40, v39
	v_fmac_f32_e32 v40, v41, v38
	v_fma_f32 v37, -v37, v40, v39
	v_div_fmas_f32 v37, v37, v38, v40
	v_div_fixup_f32 v32, v37, v32, v33
	v_mul_f32_e32 v33, v35, v36
	v_add_u32_e32 v35, 0x1000, v223
	ds_write2_b32 v35, v32, v33 offset0:128 offset1:160
	v_mul_f32_e32 v32, v34, v36
	ds_write_b32 v223, v32 offset:4864
	s_branch .LBB0_522

.LBB0_1227:
	s_lshl_b64 s[12:13], s[16:17], 19
	s_ashr_i32 s17, s18, 6
	s_mul_i32 s18, s17, 0x1400
	s_add_i32 s18, s18, 0
	s_add_i32 s45, s18, 0x1b000
	s_lshl_b32 s18, s88, 7
	s_mov_b32 s19, s1
	v_lshl_add_u64 v[8:9], v[4:5], 0, s[18:19]
	v_lshl_add_u64 v[10:11], v[2:3], 0, s[18:19]
	s_or_b32 s36, s18, 0x2000
	s_mov_b32 s37, s1
	s_lshl_b32 s44, s0, 22
	global_load_dwordx4 v[98:101], v[8:9], off nt
	global_load_dwordx4 v[102:105], v[10:11], off nt
	v_lshl_add_u64 v[8:9], v[4:5], 0, s[36:37]
	v_lshl_add_u64 v[10:11], v[2:3], 0, s[36:37]
	s_or_b32 s36, s18, 0x4000
	s_or_b32 s18, s18, 0x6000
	s_lshl_b32 s63, s17, 5
	s_add_u32 s17, s22, s44
	global_load_dwordx4 v[106:109], v[8:9], off nt
	global_load_dwordx4 v[110:113], v[10:11], off nt
	v_lshl_add_u64 v[8:9], v[4:5], 0, s[36:37]
	v_lshl_add_u64 v[10:11], v[2:3], 0, s[36:37]
	v_lshl_add_u64 v[4:5], v[4:5], 0, s[18:19]
	v_lshl_add_u64 v[2:3], v[2:3], 0, s[18:19]
	s_addc_u32 s18, s23, 0
	global_load_dwordx4 v[114:117], v[8:9], off nt
	global_load_dwordx4 v[118:121], v[10:11], off nt
	s_add_u32 s12, s17, s12
	v_and_b32_e32 v10, 0x70, v0
	s_movk_i32 s17, 0x380
	v_mov_b32_e32 v96, 0
	global_load_dwordx4 v[126:129], v[4:5], off nt
	global_load_dwordx4 v[122:125], v[2:3], off nt
	s_addc_u32 s13, s18, s13
	v_and_or_b32 v2, v0, s17, v10
	v_mov_b32_e32 v3, v96
	v_lshl_add_u64 v[2:3], s[12:13], 0, v[2:3]
	s_add_i32 s12, s63, s88
	s_or_b32 s18, s12, 24
	s_ashr_i32 s19, s18, 31
	s_lshl_b64 s[18:19], s[18:19], 7
	v_lshl_add_u64 v[4:5], v[2:3], 0, s[18:19]
	s_or_b32 s18, s12, 16
	s_ashr_i32 s19, s18, 31
	s_lshl_b64 s[18:19], s[18:19], 7
	v_lshl_add_u64 v[8:9], v[2:3], 0, s[18:19]
	s_or_b32 s18, s12, 8
	s_ashr_i32 s19, s18, 31
	s_lshl_b64 s[18:19], s[18:19], 7
	s_ashr_i32 s13, s12, 31
	global_load_dwordx4 v[138:141], v[4:5], off
	global_load_dwordx4 v[142:145], v[8:9], off
	v_lshl_add_u64 v[4:5], v[2:3], 0, s[18:19]
	s_lshl_b64 s[12:13], s[12:13], 7
	v_lshl_add_u64 v[2:3], v[2:3], 0, s[12:13]
	global_load_dwordx4 v[130:133], v[4:5], off
	global_load_dwordx4 v[134:137], v[2:3], off
	v_and_b32_e32 v12, 31, v6
	v_bfe_u32 v13, v6, 5, 1
	v_lshl_add_u64 v[162:163], s[30:31], 0, v[0:1]
	v_lshl_add_u64 v[164:165], s[10:11], 0, v[0:1]
	s_movk_i32 s64, 0x90
	v_mov_b32_e32 v0, s45
	v_bfe_u32 v3, v6, 3, 3
	v_mad_u32_u24 v167, v12, s64, v0
	v_or_b32_e32 v0, 0x80, v12
	v_lshlrev_b32_e32 v1, 2, v13
	v_bfe_u32 v5, v6, 2, 2
	s_add_i32 s12, s63, 32
	v_and_b32_e32 v7, 63, v6
	v_lshrrev_b32_e32 v2, 3, v6
	v_add_u32_e32 v166, 0, v10
	v_add_u32_e32 v4, s45, v10
	v_lshl_or_b32 v158, v3, 11, v10
	v_lshl_or_b32 v160, v3, 7, v10
	v_sub_u32_e32 v169, v0, v1
	v_or3_b32 v1, v5, v1, s63
	v_and_b32_e32 v5, 16, v6
	v_lshlrev_b32_e32 v6, 2, v6
	v_or_b32_e32 v10, s12, v12
	s_add_i32 s12, s63, 64
	v_and_or_b32 v5, v6, 12, v5
	v_or_b32_e32 v11, s12, v12
	s_add_i32 s12, s63, 0x60
	v_mul_lo_u32 v1, v1, s64
	v_lshlrev_b32_e32 v5, 1, v5
	v_or_b32_e32 v14, s12, v12
	s_add_i32 s12, s63, 0x80
	v_lshlrev_b32_e32 v168, 4, v13
	v_add3_u32 v170, 0, v1, v5
	v_mul_i32_i24_e32 v1, 0xffffff74, v12
	v_mul_lo_u32 v172, v2, s64
	v_or_b32_e32 v9, s63, v12
	v_or_b32_e32 v15, s12, v12
	v_mul_u32_u24_e32 v13, 0x240, v13
	v_lshlrev_b32_e32 v12, 1, v12
	v_add_u32_e32 v0, 0, v168
	v_cmp_gt_u32_e64 s[10:11], 32, v7
	v_add_u32_e32 v2, 0x4800, v172
	v_add_u32_e32 v5, 0x6c00, v172
	v_add_u32_e32 v6, 0x9000, v172
	v_add_u32_e32 v7, 0xb400, v172
	v_mul_u32_u24_e32 v8, 0x90, v3
	v_mul_lo_u32 v9, v9, s64
	v_mul_lo_u32 v10, v10, s64
	v_mul_lo_u32 v11, v11, s64
	v_mul_lo_u32 v14, v14, s64
	v_mul_lo_u32 v15, v15, s64
	v_add3_u32 v173, s45, v13, v12
	v_lshl_add_u32 v174, v3, 2, s45
	s_mov_b32 s18, 2.0
	s_mov_b32 s30, 0x41000000
	s_mov_b32 s36, 0x41200000
	s_mov_b32 s44, 0x41800000
	s_mov_b32 s46, 0x41900000
	s_mov_b32 s48, 0x41c00000
	s_mov_b32 s52, 0x41d00000
	v_mov_b32_e32 v161, v96
	s_movk_i32 s65, 0x80
	v_add_u32_e32 v171, 0xd800, v170
	v_mov_b32_e32 v159, v96
	s_mov_b64 s[54:55], -1
	v_add_u32_e32 v175, v166, v2
	v_add_u32_e32 v176, v166, v5
	v_add_u32_e32 v177, v166, v6
	v_add_u32_e32 v178, v166, v7
	s_mov_b32 s66, 0xc2fc0000
	v_add_u32_e32 v179, v0, v9
	s_mov_b32 s67, 0xff800000
	v_add_u32_e32 v181, v0, v10
	v_add_u32_e32 v184, v0, v11
	v_add_u32_e32 v185, v0, v14
	v_add_u32_e32 v186, v0, v15
	s_mov_b32 s19, 0x40400000
	s_mov_b32 s31, 0x41100000
	s_mov_b32 s37, 0x41300000
	s_mov_b32 s45, 0x41880000
	s_mov_b32 s47, 0x41980000
	s_mov_b32 s49, 0x41c80000
	s_mov_b32 s53, 0x41d80000
	s_movk_i32 s68, 0x81
	s_movk_i32 s69, 0x82
	s_movk_i32 s70, 0x83
	s_movk_i32 s71, 0x88
	s_movk_i32 s72, 0x89
	s_movk_i32 s73, 0x8a
	s_movk_i32 s74, 0x8b
	s_movk_i32 s75, 0x91
	s_movk_i32 s76, 0x92
	s_movk_i32 s77, 0x93
	s_movk_i32 s82, 0x98
	s_movk_i32 s83, 0x99
	s_movk_i32 s84, 0x9a
	s_movk_i32 s85, 0x9b
	v_mbcnt_hi_u32_b32 v187, -1, v183
	v_add_u32_e32 v188, v167, v1
	v_add_u32_e32 v189, v4, v8
	v_mov_b32_e32 v190, 0x42800000
	v_mov_b32_e32 v191, 0xff800000
	s_waitcnt vmcnt(0)
	s_branch .LBB0_1229

.LBB0_1231:
	s_add_i32 s12, s0, 1
	v_cvt_f32_u32_e32 v4, s12
	v_mul_f32_e32 v0, -0.5, v4
	v_cmp_gt_f32_e64 s[12:13], s66, v0
	s_and_b64 s[54:55], s[12:13], exec
	s_cselect_b32 s17, 0xffffffc0, 0
	s_lshl_b64 s[54:55], s[0:1], 2
	s_add_u32 s54, s50, s54
	s_addc_u32 s55, s51, s55
	s_load_dword s98, s[54:55], 0x0
	s_lshr_b32 s54, s62, 2
	s_mul_i32 s54, s54, s42
	s_add_i32 s56, s54, s2
	s_cmpk_gt_i32 s56, 0x1ff
	s_cselect_b64 s[58:59], -1, 0
	s_and_b32 s57, s62, 3
	s_cmp_eq_u32 s57, 0
	s_cselect_b64 s[54:55], -1, 0
	s_lshl_b32 s60, s56, 8
	s_and_b32 s86, s60, 0xf00
	s_lshr_b32 s60, s56, 2
	s_and_b32 s60, s60, 12
	s_or_b32 s87, s60, s57
	s_ashr_i32 s56, s56, 6
	s_and_b64 vcc, exec, s[58:59]
	s_waitcnt vmcnt(4)
	ds_write_b128 v189, v[134:137]
	ds_write_b128 v189, v[130:133] offset:1152
	ds_write_b128 v189, v[142:145] offset:2304
	ds_write_b128 v189, v[138:141] offset:3456
	s_cbranch_vccnz .LBB0_1240
	s_andn2_b64 vcc, exec, s[54:55]
	s_ashr_i32 s57, s56, 31
	s_cbranch_vccnz .LBB0_1239
	s_lshl_b32 s79, s60, 19
	s_lshl_b64 s[60:61], s[56:57], 18
	s_add_u32 s90, s60, s79
	s_addc_u32 s91, s61, 0
	s_cmp_lg_u32 s86, 0
	s_cselect_b64 s[60:61], -1, 0
	s_lshl_b64 s[90:91], s[90:91], 1
	s_cmp_eq_u32 s86, 0
	v_lshl_add_u64 v[0:1], v[162:163], 0, s[90:91]
	v_lshl_add_u64 v[2:3], v[164:165], 0, s[90:91]
	s_cbranch_scc1 .LBB0_1236
	s_lshl_b32 s79, s86, 7
	s_add_u32 s90, s79, 0xffffc000
	s_addc_u32 s91, 0, -1
	v_lshl_add_u64 v[6:7], v[0:1], 0, s[90:91]
	v_lshl_add_u64 v[8:9], v[2:3], 0, s[90:91]
	global_load_dwordx4 v[84:87], v[6:7], off nt
	global_load_dwordx4 v[80:83], v[8:9], off nt
	s_andn2_b64 vcc, exec, s[60:61]
	s_cbranch_vccnz .LBB0_1237

.LBB0_1240:
	s_waitcnt lgkmcnt(0)
	s_barrier
	v_mov_b32_e32 v5, s98
	v_cndmask_b32_e64 v0, 0, v190, s[12:13]
	v_fmac_f32_e32 v0, -0.5, v4
	v_exp_f32_e32 v0, v0
	s_add_i32 s12, s88, s63
	v_mul_f32_e32 v97, 0x3fb8aa3b, v5
	v_ldexp_f32 v0, v0, s17
	v_mul_f32_e32 v72, 0x3fb8aa3b, v0
	v_add_u32_e32 v0, v167, v168
	v_mov_b32_e32 v214, v169
	ds_read_b128 v[192:195], v0
	ds_read_b128 v[154:157], v0 offset:32
	ds_read_b128 v[150:153], v0 offset:64
	ds_read_b128 v[146:149], v0 offset:96
	s_cmpk_gt_i32 s12, 0x7f
	v_cvt_f32_i32_e32 v0, v214
	v_mul_f32_e32 v9, 0, v72
	s_cselect_b64 vcc, -1, 0
	v_cndmask_b32_e32 v10, v191, v9, vcc
	v_mul_f32_e64 v8, -v72, v0
	v_fma_f32 v205, -v72, v0, v72
	ds_read_b128 v[0:3], v179
	ds_read_b128 v[4:7], v179 offset:32
	v_fma_f32 v204, 0, v72, v8
	v_pk_fma_f32 v[206:207], v[72:73], s[18:19], v[8:9] op_sel_hi:[0,1,0]
	v_pk_fma_f32 v[208:209], v[72:73], s[30:31], v[8:9] op_sel_hi:[0,1,0]
	v_pk_fma_f32 v[210:211], v[72:73], s[36:37], v[8:9] op_sel_hi:[0,1,0]
	v_pk_fma_f32 v[212:213], v[72:73], s[44:45], v[8:9] op_sel_hi:[0,1,0]
	v_pk_fma_f32 v[74:75], v[72:73], s[46:47], v[8:9] op_sel_hi:[0,1,0]
	v_pk_fma_f32 v[76:77], v[72:73], s[48:49], v[8:9] op_sel_hi:[0,1,0]
	v_pk_fma_f32 v[78:79], v[72:73], s[52:53], v[8:9] op_sel_hi:[0,1,0]
	v_pk_add_f32 v[62:63], v[10:11], v[78:79] op_sel_hi:[0,1]
	v_pk_add_f32 v[60:61], v[10:11], v[76:77] op_sel_hi:[0,1]
	v_pk_add_f32 v[58:59], v[10:11], v[74:75] op_sel_hi:[0,1]
	v_pk_add_f32 v[56:57], v[10:11], v[212:213] op_sel_hi:[0,1]
	v_pk_add_f32 v[54:55], v[10:11], v[210:211] op_sel_hi:[0,1]
	v_pk_add_f32 v[52:53], v[10:11], v[208:209] op_sel_hi:[0,1]
	v_pk_add_f32 v[50:51], v[10:11], v[206:207] op_sel_hi:[0,1]
	v_pk_add_f32 v[48:49], v[10:11], v[204:205] op_sel_hi:[0,1]
	s_cmpk_gt_i32 s12, 0x5f
	v_mul_f32_e32 v12, 0x42000000, v72
	s_waitcnt lgkmcnt(1)
	v_mfma_f32_32x32x16_bf16 v[48:63], v[0:3], v[192:195], v[48:63]
	s_cselect_b64 vcc, -1, 0
	v_cndmask_b32_e32 v12, v191, v12, vcc
	v_add_f32_e64 v46, v12, v78
	v_add_f32_e64 v47, v12, v79
	v_add_f32_e64 v44, v12, v76
	v_add_f32_e64 v45, v12, v77
	v_pk_add_f32 v[42:43], v[12:13], v[74:75] op_sel_hi:[0,1]
	v_pk_add_f32 v[40:41], v[12:13], v[212:213] op_sel_hi:[0,1]
	v_pk_add_f32 v[38:39], v[12:13], v[210:211] op_sel_hi:[0,1]
	s_waitcnt lgkmcnt(0)
	v_mfma_f32_32x32x16_bf16 v[48:63], v[4:7], v[154:157], v[48:63]
	ds_read_b128 v[0:3], v179 offset:64
	ds_read_b128 v[4:7], v179 offset:96
	v_add_f32_e64 v36, v12, v208
	v_add_f32_e64 v37, v12, v209
	v_add_f32_e64 v34, v12, v206
	v_add_f32_e64 v35, v12, v207
	v_pk_add_f32 v[32:33], v[12:13], v[204:205] op_sel_hi:[0,1]
	s_cmp_gt_i32 s12, 63
	v_mul_f32_e32 v12, 0x42800000, v72
	s_cselect_b64 vcc, -1, 0
	s_waitcnt lgkmcnt(1)
	v_mfma_f32_32x32x16_bf16 v[48:63], v[0:3], v[150:153], v[48:63]
	ds_read_b128 v[0:3], v181
	ds_read_b128 v[8:11], v181 offset:32
	v_cndmask_b32_e32 v12, v191, v12, vcc
	v_add_f32_e64 v30, v12, v78
	v_add_f32_e64 v31, v12, v79
	v_pk_add_f32 v[28:29], v[12:13], v[76:77] op_sel_hi:[0,1]
	v_pk_add_f32 v[26:27], v[12:13], v[74:75] op_sel_hi:[0,1]
	v_pk_add_f32 v[24:25], v[12:13], v[212:213] op_sel_hi:[0,1]
	v_pk_add_f32 v[22:23], v[12:13], v[210:211] op_sel_hi:[0,1]
	s_waitcnt lgkmcnt(1)
	v_mfma_f32_32x32x16_bf16 v[32:47], v[0:3], v[192:195], v[32:47]
	v_add_f32_e64 v20, v12, v208
	v_add_f32_e64 v21, v12, v209
	v_add_f32_e64 v18, v12, v206
	v_add_f32_e64 v19, v12, v207
	v_add_f32_e64 v16, v12, v204
	v_add_f32_e64 v17, v12, v205
	s_cmp_gt_i32 s12, 31
	s_cselect_b64 vcc, -1, 0
	s_cmp_gt_i32 s12, -1
	s_waitcnt lgkmcnt(0)
	v_mfma_f32_32x32x16_bf16 v[32:47], v[8:11], v[154:157], v[32:47]
	v_mfma_f32_32x32x16_bf16 v[48:63], v[4:7], v[146:149], v[48:63]
	ds_read_b128 v[0:3], v181 offset:64
	ds_read_b128 v[4:7], v181 offset:96
	s_waitcnt lgkmcnt(1)
	v_mfma_f32_32x32x16_bf16 v[32:47], v[0:3], v[150:153], v[32:47]
	ds_read_b128 v[0:3], v184
	ds_read_b128 v[8:11], v184 offset:32
	s_waitcnt lgkmcnt(1)
	v_mfma_f32_32x32x16_bf16 v[16:31], v[0:3], v[192:195], v[16:31]
	s_waitcnt lgkmcnt(0)
	v_mfma_f32_32x32x16_bf16 v[16:31], v[8:11], v[154:157], v[16:31]
	v_mfma_f32_32x32x16_bf16 v[32:47], v[4:7], v[146:149], v[32:47]
	ds_read_b128 v[0:3], v184 offset:64
	ds_read_b128 v[4:7], v184 offset:96
	ds_read_b128 v[64:67], v185
	ds_read_b128 v[68:71], v185 offset:32
	s_waitcnt lgkmcnt(3)
	v_mfma_f32_32x32x16_bf16 v[16:31], v[0:3], v[150:153], v[16:31]
	v_mul_f32_e32 v0, 0x42c00000, v72
	v_cndmask_b32_e32 v0, v191, v0, vcc
	v_add_f32_e64 v14, v0, v78
	v_add_f32_e64 v15, v0, v79
	v_add_f32_e64 v12, v0, v76
	v_add_f32_e64 v13, v0, v77
	v_pk_add_f32 v[10:11], v[0:1], v[74:75] op_sel_hi:[0,1]
	v_pk_add_f32 v[8:9], v[0:1], v[212:213] op_sel_hi:[0,1]
	v_pk_add_f32 v[2:3], v[0:1], v[206:207] op_sel_hi:[0,1]
	s_waitcnt lgkmcnt(2)
	v_mfma_f32_32x32x16_bf16 v[16:31], v[4:7], v[146:149], v[16:31]
	v_add_f32_e64 v6, v0, v210
	v_add_f32_e64 v7, v0, v211
	v_add_f32_e64 v4, v0, v208
	v_add_f32_e64 v5, v0, v209
	v_pk_add_f32 v[0:1], v[0:1], v[204:205] op_sel_hi:[0,1]
	s_cselect_b64 vcc, -1, 0
	s_waitcnt lgkmcnt(1)
	v_mfma_f32_32x32x16_bf16 v[0:15], v[64:67], v[192:195], v[0:15]
	s_waitcnt lgkmcnt(0)
	v_mfma_f32_32x32x16_bf16 v[0:15], v[68:71], v[154:157], v[0:15]
	ds_read_b128 v[64:67], v185 offset:64
	ds_read_b128 v[68:71], v185 offset:96
	ds_read_b128 v[196:199], v186
	ds_read_b128 v[200:203], v186 offset:32
	s_waitcnt lgkmcnt(3)
	v_mfma_f32_32x32x16_bf16 v[0:15], v[64:67], v[150:153], v[0:15]
	v_mul_f32_e32 v64, 0x43000000, v72
	v_cndmask_b32_e32 v64, v191, v64, vcc
	v_add_f32_e64 v78, v64, v78
	v_add_f32_e64 v79, v64, v79
	v_add_f32_e64 v76, v64, v76
	v_add_f32_e64 v77, v64, v77
	v_pk_add_f32 v[74:75], v[64:65], v[74:75] op_sel_hi:[0,1]
	v_pk_add_f32 v[72:73], v[64:65], v[212:213] op_sel_hi:[0,1]
	v_pk_add_f32 v[66:67], v[64:65], v[206:207] op_sel_hi:[0,1]
	s_waitcnt lgkmcnt(2)
	v_mfma_f32_32x32x16_bf16 v[0:15], v[68:71], v[146:149], v[0:15]
	v_add_f32_e64 v70, v64, v210
	v_add_f32_e64 v71, v64, v211
	v_add_f32_e64 v68, v64, v208
	v_add_f32_e64 v69, v64, v209
	v_pk_add_f32 v[64:65], v[64:65], v[204:205] op_sel_hi:[0,1]
	s_waitcnt lgkmcnt(1)
	s_nop 0
	v_mfma_f32_32x32x16_bf16 v[64:79], v[196:199], v[192:195], v[64:79]
	s_waitcnt lgkmcnt(0)
	v_mfma_f32_32x32x16_bf16 v[64:79], v[200:203], v[154:157], v[64:79]
	ds_read_b128 v[154:157], v186 offset:64
	ds_read_b128 v[192:195], v186 offset:96
	s_waitcnt lgkmcnt(1)
	v_mfma_f32_32x32x16_bf16 v[64:79], v[154:157], v[150:153], v[64:79]
	s_waitcnt lgkmcnt(0)
	v_mfma_f32_32x32x16_bf16 v[64:79], v[192:195], v[146:149], v[64:79]
	v_cmp_gt_i32_e32 vcc, s65, v214
	s_nop 1
	v_cndmask_b32_e32 v48, v191, v48, vcc
	s_nop 7
	v_cndmask_b32_e32 v152, v64, v191, vcc
	v_cmp_gt_i32_e32 vcc, s68, v214
	s_nop 1
	v_cndmask_b32_e32 v49, v191, v49, vcc
	v_cndmask_b32_e32 v153, v65, v191, vcc
	v_cmp_gt_i32_e32 vcc, s69, v214
	v_max3_f32 v64, v48, s67, v49
	s_nop 0
	v_cndmask_b32_e32 v50, v191, v50, vcc
	v_cndmask_b32_e32 v150, v66, v191, vcc
	v_cmp_gt_i32_e32 vcc, s70, v214
	s_nop 1
	v_cndmask_b32_e32 v51, v191, v51, vcc
	v_cndmask_b32_e32 v151, v67, v191, vcc
	v_cmp_gt_i32_e32 vcc, s71, v214
	v_max3_f32 v64, v64, v50, v51
	s_nop 0
	v_cndmask_b32_e32 v52, v191, v52, vcc
	v_cndmask_b32_e32 v148, v68, v191, vcc
	v_cmp_gt_i32_e32 vcc, s72, v214
	s_nop 1
	v_cndmask_b32_e32 v53, v191, v53, vcc
	v_cndmask_b32_e32 v149, v69, v191, vcc
	v_cmp_gt_i32_e32 vcc, s73, v214
	v_max3_f32 v64, v64, v52, v53
	s_nop 0
	v_cndmask_b32_e32 v54, v191, v54, vcc
	v_cndmask_b32_e32 v146, v70, v191, vcc
	v_cmp_gt_i32_e32 vcc, s74, v214
	s_nop 1
	v_cndmask_b32_e32 v55, v191, v55, vcc
	v_cndmask_b32_e32 v147, v71, v191, vcc
	v_cmp_gt_i32_e32 vcc, s64, v214
	v_max3_f32 v64, v64, v54, v55
	s_nop 0
	v_cndmask_b32_e32 v56, v191, v56, vcc
	v_cndmask_b32_e32 v72, v72, v191, vcc
	v_cmp_gt_i32_e32 vcc, s75, v214
	s_nop 1
	v_cndmask_b32_e32 v57, v191, v57, vcc
	v_cndmask_b32_e32 v73, v73, v191, vcc
	v_cmp_gt_i32_e32 vcc, s76, v214
	v_max3_f32 v64, v64, v56, v57
	s_nop 0
	v_cndmask_b32_e32 v58, v191, v58, vcc
	v_cndmask_b32_e32 v70, v74, v191, vcc
	v_cmp_gt_i32_e32 vcc, s77, v214
	s_nop 1
	v_cndmask_b32_e32 v59, v191, v59, vcc
	v_cndmask_b32_e32 v71, v75, v191, vcc
	v_cmp_gt_i32_e32 vcc, s82, v214
	v_max3_f32 v64, v64, v58, v59
	s_nop 0
	v_cndmask_b32_e32 v60, v191, v60, vcc
	v_cndmask_b32_e32 v68, v76, v191, vcc
	v_cmp_gt_i32_e32 vcc, s83, v214
	s_nop 1
	v_cndmask_b32_e32 v61, v191, v61, vcc
	v_cndmask_b32_e32 v69, v77, v191, vcc
	v_cmp_gt_i32_e32 vcc, s84, v214
	v_max3_f32 v64, v64, v60, v61
	s_nop 0
	v_cndmask_b32_e32 v62, v191, v62, vcc
	v_cndmask_b32_e32 v66, v78, v191, vcc
	v_cmp_gt_i32_e32 vcc, s85, v214
	s_nop 1
	v_cndmask_b32_e32 v63, v191, v63, vcc
	v_max3_f32 v64, v64, v62, v63
	v_max3_f32 v64, v64, v32, v33
	v_max3_f32 v64, v64, v34, v35
	v_max3_f32 v64, v64, v36, v37
	v_max3_f32 v64, v64, v38, v39
	v_max3_f32 v64, v64, v40, v41
	v_max3_f32 v64, v64, v42, v43
	v_max3_f32 v64, v64, v44, v45
	v_max3_f32 v64, v64, v46, v47
	v_max3_f32 v64, v64, v16, v17
	v_max3_f32 v64, v64, v18, v19
	v_max3_f32 v64, v64, v20, v21
	v_max3_f32 v64, v64, v22, v23
	v_max3_f32 v64, v64, v24, v25
	v_max3_f32 v64, v64, v26, v27
	v_max3_f32 v64, v64, v28, v29
	v_max3_f32 v64, v64, v30, v31
	v_max3_f32 v64, v64, v0, v1
	v_max3_f32 v64, v64, v2, v3
	v_max3_f32 v64, v64, v4, v5
	v_max3_f32 v64, v64, v6, v7
	v_max3_f32 v64, v64, v8, v9
	v_max3_f32 v64, v64, v10, v11
	v_max3_f32 v64, v64, v12, v13
	v_max3_f32 v64, v64, v14, v15
	v_max3_f32 v64, v64, v152, v153
	v_max3_f32 v64, v64, v150, v151
	v_max3_f32 v64, v64, v148, v149
	v_max3_f32 v64, v64, v146, v147
	v_max3_f32 v64, v64, v72, v73
	v_max3_f32 v64, v64, v70, v71
	v_cndmask_b32_e32 v67, v79, v191, vcc
	v_max3_f32 v64, v64, v68, v69
	v_max3_f32 v64, v64, v66, v67
	v_and_b32_e32 v74, 64, v187
	v_xor_b32_e32 v65, 32, v187
	v_add_u32_e32 v74, 64, v74
	v_cmp_lt_i32_e32 vcc, v65, v74
	s_nop 1
	v_cndmask_b32_e32 v65, v187, v65, vcc
	v_lshlrev_b32_e32 v65, 2, v65
	ds_bpermute_b32 v74, v65, v64
	s_waitcnt lgkmcnt(0)
	v_max3_f32 v64, v64, v74, v97
	v_pk_add_f32 v[48:49], v[48:49], v[64:65] op_sel_hi:[1,0] neg_lo:[0,1] neg_hi:[0,1]
	v_pk_add_f32 v[50:51], v[50:51], v[64:65] op_sel_hi:[1,0] neg_lo:[0,1] neg_hi:[0,1]
	v_exp_f32_e32 v48, v48
	v_exp_f32_e32 v49, v49
	v_exp_f32_e32 v50, v50
	v_exp_f32_e32 v51, v51
	v_pk_add_f32 v[52:53], v[52:53], v[64:65] op_sel_hi:[1,0] neg_lo:[0,1] neg_hi:[0,1]
	v_pk_add_f32 v[54:55], v[54:55], v[64:65] op_sel_hi:[1,0] neg_lo:[0,1] neg_hi:[0,1]
	v_exp_f32_e32 v52, v52
	v_exp_f32_e32 v53, v53
	v_exp_f32_e32 v54, v54
	v_exp_f32_e32 v55, v55
	v_pk_add_f32 v[56:57], v[56:57], v[64:65] op_sel_hi:[1,0] neg_lo:[0,1] neg_hi:[0,1]
	v_pk_add_f32 v[74:75], v[48:49], 0 op_sel_hi:[1,0]
	v_exp_f32_e32 v56, v56
	v_exp_f32_e32 v57, v57
	v_pk_add_f32 v[74:75], v[50:51], v[74:75]
	v_cvt_pk_bf16_f32 v48, v48, v49
	v_cvt_pk_bf16_f32 v49, v50, v51
	v_cvt_pk_bf16_f32 v50, v52, v53
	v_pk_add_f32 v[58:59], v[58:59], v[64:65] op_sel_hi:[1,0] neg_lo:[0,1] neg_hi:[0,1]
	v_pk_add_f32 v[74:75], v[52:53], v[74:75]
	v_exp_f32_e32 v58, v58
	v_pk_add_f32 v[52:53], v[54:55], v[74:75]
	v_exp_f32_e32 v59, v59
	v_cvt_pk_bf16_f32 v51, v54, v55
	v_pk_add_f32 v[54:55], v[56:57], v[52:53]
	v_cvt_pk_bf16_f32 v52, v56, v57
	v_pk_add_f32 v[56:57], v[60:61], v[64:65] op_sel_hi:[1,0] neg_lo:[0,1] neg_hi:[0,1]
	v_pk_add_f32 v[60:61], v[62:63], v[64:65] op_sel_hi:[1,0] neg_lo:[0,1] neg_hi:[0,1]
	v_exp_f32_e32 v56, v56
	v_exp_f32_e32 v57, v57
	v_exp_f32_e32 v60, v60
	v_exp_f32_e32 v61, v61
	v_pk_add_f32 v[54:55], v[58:59], v[54:55]
	v_cvt_pk_bf16_f32 v53, v58, v59
	s_nop 0
	v_pk_add_f32 v[58:59], v[56:57], v[54:55]
	v_cvt_pk_bf16_f32 v54, v56, v57
	v_cvt_pk_bf16_f32 v55, v60, v61
	s_nop 0
	v_pk_add_f32 v[56:57], v[60:61], v[58:59]
	v_pk_add_f32 v[32:33], v[32:33], v[64:65] op_sel_hi:[1,0] neg_lo:[0,1] neg_hi:[0,1]
	v_pk_add_f32 v[34:35], v[34:35], v[64:65] op_sel_hi:[1,0] neg_lo:[0,1] neg_hi:[0,1]
	v_exp_f32_e32 v32, v32
	v_exp_f32_e32 v33, v33
	v_exp_f32_e32 v34, v34
	v_exp_f32_e32 v35, v35
	v_pk_add_f32 v[36:37], v[36:37], v[64:65] op_sel_hi:[1,0] neg_lo:[0,1] neg_hi:[0,1]
	v_pk_add_f32 v[38:39], v[38:39], v[64:65] op_sel_hi:[1,0] neg_lo:[0,1] neg_hi:[0,1]
	v_exp_f32_e32 v36, v36
	v_exp_f32_e32 v37, v37
	v_exp_f32_e32 v38, v38
	v_exp_f32_e32 v39, v39
	v_pk_add_f32 v[40:41], v[40:41], v[64:65] op_sel_hi:[1,0] neg_lo:[0,1] neg_hi:[0,1]
	v_pk_add_f32 v[56:57], v[32:33], v[56:57]
	v_exp_f32_e32 v40, v40
	v_exp_f32_e32 v41, v41
	v_pk_add_f32 v[56:57], v[34:35], v[56:57]
	v_cvt_pk_bf16_f32 v32, v32, v33
	v_cvt_pk_bf16_f32 v33, v34, v35
	v_cvt_pk_bf16_f32 v34, v36, v37
	v_pk_add_f32 v[42:43], v[42:43], v[64:65] op_sel_hi:[1,0] neg_lo:[0,1] neg_hi:[0,1]
	v_pk_add_f32 v[56:57], v[36:37], v[56:57]
	v_exp_f32_e32 v42, v42
	v_pk_add_f32 v[36:37], v[38:39], v[56:57]
	v_exp_f32_e32 v43, v43
	v_cvt_pk_bf16_f32 v35, v38, v39
	v_pk_add_f32 v[38:39], v[40:41], v[36:37]
	v_cvt_pk_bf16_f32 v36, v40, v41
	v_pk_add_f32 v[40:41], v[44:45], v[64:65] op_sel_hi:[1,0] neg_lo:[0,1] neg_hi:[0,1]
	v_pk_add_f32 v[44:45], v[46:47], v[64:65] op_sel_hi:[1,0] neg_lo:[0,1] neg_hi:[0,1]
	v_exp_f32_e32 v40, v40
	v_exp_f32_e32 v41, v41
	v_exp_f32_e32 v44, v44
	v_exp_f32_e32 v45, v45
	v_pk_add_f32 v[38:39], v[42:43], v[38:39]
	v_cvt_pk_bf16_f32 v37, v42, v43
	s_nop 0
	v_pk_add_f32 v[42:43], v[40:41], v[38:39]
	v_cvt_pk_bf16_f32 v38, v40, v41
	v_cvt_pk_bf16_f32 v39, v44, v45
	s_nop 0
	v_pk_add_f32 v[40:41], v[44:45], v[42:43]
	v_pk_add_f32 v[16:17], v[16:17], v[64:65] op_sel_hi:[1,0] neg_lo:[0,1] neg_hi:[0,1]
	v_pk_add_f32 v[18:19], v[18:19], v[64:65] op_sel_hi:[1,0] neg_lo:[0,1] neg_hi:[0,1]
	v_exp_f32_e32 v16, v16
	v_exp_f32_e32 v17, v17
	v_exp_f32_e32 v18, v18
	v_exp_f32_e32 v19, v19
	v_pk_add_f32 v[20:21], v[20:21], v[64:65] op_sel_hi:[1,0] neg_lo:[0,1] neg_hi:[0,1]
	v_pk_add_f32 v[42:43], v[16:17], v[40:41]
	v_exp_f32_e32 v20, v20
	v_exp_f32_e32 v21, v21
	v_pk_add_f32 v[22:23], v[22:23], v[64:65] op_sel_hi:[1,0] neg_lo:[0,1] neg_hi:[0,1]
	v_cvt_pk_bf16_f32 v40, v16, v17
	v_pk_add_f32 v[16:17], v[18:19], v[42:43]
	v_exp_f32_e32 v22, v22
	v_exp_f32_e32 v23, v23
	v_cvt_pk_bf16_f32 v41, v18, v19
	v_pk_add_f32 v[18:19], v[24:25], v[64:65] op_sel_hi:[1,0] neg_lo:[0,1] neg_hi:[0,1]
	v_pk_add_f32 v[16:17], v[20:21], v[16:17]
	v_exp_f32_e32 v18, v18
	v_exp_f32_e32 v19, v19
	v_cvt_pk_bf16_f32 v42, v20, v21
	v_pk_add_f32 v[16:17], v[22:23], v[16:17]
	v_pk_add_f32 v[20:21], v[26:27], v[64:65] op_sel_hi:[1,0] neg_lo:[0,1] neg_hi:[0,1]
	v_cvt_pk_bf16_f32 v43, v22, v23
	v_pk_add_f32 v[16:17], v[18:19], v[16:17]
	v_exp_f32_e32 v20, v20
	v_exp_f32_e32 v21, v21
	v_cvt_pk_bf16_f32 v44, v18, v19
	v_pk_add_f32 v[18:19], v[28:29], v[64:65] op_sel_hi:[1,0] neg_lo:[0,1] neg_hi:[0,1]
	v_pk_add_f32 v[22:23], v[30:31], v[64:65] op_sel_hi:[1,0] neg_lo:[0,1] neg_hi:[0,1]
	v_exp_f32_e32 v18, v18
	v_exp_f32_e32 v19, v19
	v_exp_f32_e32 v22, v22
	v_exp_f32_e32 v23, v23
	v_pk_add_f32 v[16:17], v[20:21], v[16:17]
	v_cvt_pk_bf16_f32 v45, v20, v21
	v_cvt_pk_bf16_f32 v46, v18, v19
	v_cvt_pk_bf16_f32 v47, v22, v23
	s_nop 0
	v_pk_add_f32 v[16:17], v[18:19], v[16:17]
	s_nop 0
	v_pk_add_f32 v[16:17], v[22:23], v[16:17]
	v_pk_add_f32 v[0:1], v[0:1], v[64:65] op_sel_hi:[1,0] neg_lo:[0,1] neg_hi:[0,1]
	v_pk_add_f32 v[2:3], v[2:3], v[64:65] op_sel_hi:[1,0] neg_lo:[0,1] neg_hi:[0,1]
	v_exp_f32_e32 v0, v0
	v_exp_f32_e32 v1, v1
	v_exp_f32_e32 v2, v2
	v_exp_f32_e32 v3, v3
	v_pk_add_f32 v[4:5], v[4:5], v[64:65] op_sel_hi:[1,0] neg_lo:[0,1] neg_hi:[0,1]
	v_pk_add_f32 v[16:17], v[0:1], v[16:17]
	v_exp_f32_e32 v4, v4
	v_exp_f32_e32 v5, v5
	v_pk_add_f32 v[6:7], v[6:7], v[64:65] op_sel_hi:[1,0] neg_lo:[0,1] neg_hi:[0,1]
	v_cvt_pk_bf16_f32 v56, v0, v1
	v_pk_add_f32 v[0:1], v[2:3], v[16:17]
	v_exp_f32_e32 v6, v6
	v_exp_f32_e32 v7, v7
	v_cvt_pk_bf16_f32 v57, v2, v3
	v_pk_add_f32 v[2:3], v[8:9], v[64:65] op_sel_hi:[1,0] neg_lo:[0,1] neg_hi:[0,1]
	v_pk_add_f32 v[0:1], v[4:5], v[0:1]
	v_exp_f32_e32 v2, v2
	v_exp_f32_e32 v3, v3
	v_cvt_pk_bf16_f32 v58, v4, v5
	v_pk_add_f32 v[0:1], v[6:7], v[0:1]
	v_pk_add_f32 v[4:5], v[10:11], v[64:65] op_sel_hi:[1,0] neg_lo:[0,1] neg_hi:[0,1]
	v_cvt_pk_bf16_f32 v59, v6, v7
	v_pk_add_f32 v[0:1], v[2:3], v[0:1]
	v_exp_f32_e32 v4, v4
	v_exp_f32_e32 v5, v5
	v_cvt_pk_bf16_f32 v60, v2, v3
	v_pk_add_f32 v[2:3], v[12:13], v[64:65] op_sel_hi:[1,0] neg_lo:[0,1] neg_hi:[0,1]
	v_pk_add_f32 v[6:7], v[14:15], v[64:65] op_sel_hi:[1,0] neg_lo:[0,1] neg_hi:[0,1]
	v_exp_f32_e32 v2, v2
	v_exp_f32_e32 v3, v3
	v_exp_f32_e32 v6, v6
	v_exp_f32_e32 v7, v7
	v_pk_add_f32 v[0:1], v[4:5], v[0:1]
	v_cvt_pk_bf16_f32 v61, v4, v5
	v_cvt_pk_bf16_f32 v62, v2, v3
	v_cvt_pk_bf16_f32 v63, v6, v7
	s_nop 0
	v_pk_add_f32 v[0:1], v[2:3], v[0:1]
	s_nop 0
	v_pk_add_f32 v[0:1], v[6:7], v[0:1]
	v_pk_add_f32 v[2:3], v[152:153], v[64:65] op_sel_hi:[1,0] neg_lo:[0,1] neg_hi:[0,1]
	v_pk_add_f32 v[4:5], v[150:151], v[64:65] op_sel_hi:[1,0] neg_lo:[0,1] neg_hi:[0,1]
	v_exp_f32_e32 v2, v2
	v_exp_f32_e32 v3, v3
	v_exp_f32_e32 v4, v4
	v_exp_f32_e32 v5, v5
	v_cvt_pk_bf16_f32 v74, v2, v3
	v_pk_add_f32 v[0:1], v[2:3], v[0:1]
	v_pk_add_f32 v[2:3], v[148:149], v[64:65] op_sel_hi:[1,0] neg_lo:[0,1] neg_hi:[0,1]
	v_pk_add_f32 v[0:1], v[4:5], v[0:1]
	v_exp_f32_e32 v2, v2
	v_exp_f32_e32 v3, v3
	v_pk_add_f32 v[6:7], v[146:147], v[64:65] op_sel_hi:[1,0] neg_lo:[0,1] neg_hi:[0,1]
	v_cvt_pk_bf16_f32 v75, v4, v5
	v_cvt_pk_bf16_f32 v76, v2, v3
	v_pk_add_f32 v[0:1], v[2:3], v[0:1]
	v_exp_f32_e32 v6, v6
	v_exp_f32_e32 v7, v7
	v_pk_add_f32 v[2:3], v[72:73], v[64:65] op_sel_hi:[1,0] neg_lo:[0,1] neg_hi:[0,1]
	v_pk_add_f32 v[4:5], v[70:71], v[64:65] op_sel_hi:[1,0] neg_lo:[0,1] neg_hi:[0,1]
	v_exp_f32_e32 v2, v2
	v_exp_f32_e32 v3, v3
	v_pk_add_f32 v[0:1], v[6:7], v[0:1]
	v_exp_f32_e32 v4, v4
	v_exp_f32_e32 v5, v5
	v_cvt_pk_bf16_f32 v77, v6, v7
	v_pk_add_f32 v[0:1], v[2:3], v[0:1]
	v_cvt_pk_bf16_f32 v70, v2, v3
	v_pk_add_f32 v[2:3], v[68:69], v[64:65] op_sel_hi:[1,0] neg_lo:[0,1] neg_hi:[0,1]
	v_pk_add_f32 v[6:7], v[66:67], v[64:65] op_sel_hi:[1,0] neg_lo:[0,1] neg_hi:[0,1]
	v_exp_f32_e32 v2, v2
	v_exp_f32_e32 v3, v3
	v_exp_f32_e32 v6, v6
	v_exp_f32_e32 v7, v7
	v_pk_add_f32 v[0:1], v[4:5], v[0:1]
	v_cvt_pk_bf16_f32 v71, v4, v5
	v_cvt_pk_bf16_f32 v72, v2, v3
	v_cvt_pk_bf16_f32 v73, v6, v7
	s_nop 0
	v_pk_add_f32 v[0:1], v[2:3], v[0:1]
	s_nop 0
	v_pk_add_f32 v[78:79], v[6:7], v[0:1]
	ds_read_b64_tr_b16 v[0:1], v170 offset:55296
	ds_read_b64_tr_b16 v[2:3], v170 offset:56448
	ds_read_b64_tr_b16 v[18:19], v170 offset:56512
	ds_read_b64_tr_b16 v[16:17], v170 offset:55360
	s_waitcnt lgkmcnt(2)
	v_mfma_f32_32x32x16_bf16 v[0:15], v[48:51], v[0:3], 0
	s_waitcnt lgkmcnt(0)
	v_mfma_f32_32x32x16_bf16 v[16:31], v[48:51], v[16:19], 0
	ds_read_b64_tr_b16 v[48:49], v170 offset:57600
	ds_read_b64_tr_b16 v[50:51], v170 offset:58752
	ds_read_b64_tr_b16 v[68:69], v170 offset:58816
	ds_read_b64_tr_b16 v[66:67], v170 offset:57664
	s_waitcnt lgkmcnt(2)
	v_mfma_f32_32x32x16_bf16 v[0:15], v[52:55], v[48:51], v[0:15]
	s_waitcnt lgkmcnt(0)
	v_mfma_f32_32x32x16_bf16 v[16:31], v[52:55], v[66:69], v[16:31]
	ds_read_b64_tr_b16 v[48:49], v170 offset:59904
	ds_read_b64_tr_b16 v[50:51], v170 offset:61056
	ds_read_b64_tr_b16 v[54:55], v170 offset:61120
	ds_read_b64_tr_b16 v[52:53], v170 offset:59968
	s_waitcnt lgkmcnt(2)
	v_mfma_f32_32x32x16_bf16 v[0:15], v[32:35], v[48:51], v[0:15]
	s_waitcnt lgkmcnt(0)
	v_mfma_f32_32x32x16_bf16 v[16:31], v[32:35], v[52:55], v[16:31]
	ds_read_b64_tr_b16 v[32:33], v170 offset:62208
	ds_read_b64_tr_b16 v[34:35], v170 offset:63360
	ds_read_b64_tr_b16 v[50:51], v170 offset:63424
	ds_read_b64_tr_b16 v[48:49], v170 offset:62272
	s_waitcnt lgkmcnt(2)
	v_mfma_f32_32x32x16_bf16 v[0:15], v[36:39], v[32:35], v[0:15]
	s_waitcnt lgkmcnt(0)
	v_mfma_f32_32x32x16_bf16 v[16:31], v[36:39], v[48:51], v[16:31]
	ds_read_b64_tr_b16 v[32:33], v170 offset:64512
	ds_read_b64_tr_b16 v[34:35], v171 offset:10368
	ds_read_b64_tr_b16 v[38:39], v171 offset:10432
	ds_read_b64_tr_b16 v[36:37], v170 offset:64576
	s_waitcnt lgkmcnt(2)
	v_mfma_f32_32x32x16_bf16 v[0:15], v[40:43], v[32:35], v[0:15]
	s_waitcnt lgkmcnt(0)
	v_mfma_f32_32x32x16_bf16 v[16:31], v[40:43], v[36:39], v[16:31]
	ds_read_b64_tr_b16 v[32:33], v171 offset:11520
	ds_read_b64_tr_b16 v[34:35], v171 offset:12672
	ds_read_b64_tr_b16 v[38:39], v171 offset:12736
	ds_read_b64_tr_b16 v[36:37], v171 offset:11584
	s_waitcnt lgkmcnt(2)
	v_mfma_f32_32x32x16_bf16 v[0:15], v[44:47], v[32:35], v[0:15]
	s_waitcnt lgkmcnt(0)
	v_mfma_f32_32x32x16_bf16 v[16:31], v[44:47], v[36:39], v[16:31]
	ds_read_b64_tr_b16 v[32:33], v171 offset:13824
	ds_read_b64_tr_b16 v[34:35], v171 offset:14976
	ds_read_b64_tr_b16 v[38:39], v171 offset:15040
	ds_read_b64_tr_b16 v[36:37], v171 offset:13888
	s_waitcnt lgkmcnt(2)
	v_mfma_f32_32x32x16_bf16 v[0:15], v[56:59], v[32:35], v[0:15]
	s_waitcnt lgkmcnt(0)
	v_mfma_f32_32x32x16_bf16 v[16:31], v[56:59], v[36:39], v[16:31]
	ds_read_b64_tr_b16 v[32:33], v171 offset:16128
	ds_read_b64_tr_b16 v[34:35], v171 offset:17280
	ds_read_b64_tr_b16 v[38:39], v171 offset:17344
	ds_read_b64_tr_b16 v[36:37], v171 offset:16192
	s_waitcnt lgkmcnt(2)
	v_mfma_f32_32x32x16_bf16 v[0:15], v[60:63], v[32:35], v[0:15]
	s_waitcnt lgkmcnt(0)
	v_mfma_f32_32x32x16_bf16 v[16:31], v[60:63], v[36:39], v[16:31]
	ds_read_b64_tr_b16 v[32:33], v171 offset:18432
	ds_read_b64_tr_b16 v[34:35], v171 offset:19584
	ds_read_b64_tr_b16 v[38:39], v171 offset:19648
	ds_read_b64_tr_b16 v[36:37], v171 offset:18496
	s_waitcnt lgkmcnt(2)
	v_mfma_f32_32x32x16_bf16 v[0:15], v[74:77], v[32:35], v[0:15]
	s_waitcnt lgkmcnt(0)
	v_mfma_f32_32x32x16_bf16 v[16:31], v[74:77], v[36:39], v[16:31]
	ds_read_b64_tr_b16 v[32:33], v171 offset:20736
	ds_read_b64_tr_b16 v[34:35], v171 offset:21888
	ds_read_b64_tr_b16 v[38:39], v171 offset:21952
	ds_read_b64_tr_b16 v[36:37], v171 offset:20800
	s_waitcnt lgkmcnt(2)
	v_mfma_f32_32x32x16_bf16 v[0:15], v[70:73], v[32:35], v[0:15]
	v_add_f32_e32 v32, v78, v79
	ds_bpermute_b32 v33, v65, v32
	s_waitcnt lgkmcnt(1)
	v_mfma_f32_32x32x16_bf16 v[16:31], v[70:73], v[36:39], v[16:31]
	s_and_saveexec_b64 s[60:61], s[10:11]
	s_cbranch_execz .LBB0_1228
	v_sub_f32_e32 v34, v97, v64
	v_exp_f32_e32 v34, v34
	s_waitcnt lgkmcnt(0)
	v_add_f32_e32 v32, v32, v33
	v_add_f32_e32 v32, v34, v32
	v_div_scale_f32 v33, s[88:89], v32, v32, 1.0
	v_rcp_f32_e32 v34, v33
	v_div_scale_f32 v35, vcc, 1.0, v32, 1.0
	v_fma_f32 v36, -v33, v34, 1.0
	v_fmac_f32_e32 v34, v36, v34
	v_mul_f32_e32 v36, v35, v34
	v_fma_f32 v37, -v33, v36, v35
	v_fmac_f32_e32 v36, v37, v34
	v_fma_f32 v33, -v33, v36, v35
	v_div_fmas_f32 v33, v33, v34, v36
	v_div_fixup_f32 v32, v33, v32, 1.0
	ds_write_b32 v188, v32 offset:4608
	s_branch .LBB0_1228
